# speedup vs baseline: 1.0054x; 1.0054x over previous
; __device__ __forceinline__ unsigned pk2(float lo, float hi) { const f32x2_t v = {lo, hi}; const bf16x2_t b = __builtin_convertvector(v, bf16x2_t); return __builtin_bit_cast(unsigned, b); }
; #define MFMA16(a, b, c) __builtin_amdgcn_mfma_f32_16x16x32_bf16((a), (b), (c), 0, 0, 0)
; __global__ void __launch_bounds__(512, 2) fwd_megakernel(Params kp_) {
;     ...
;                             for (int tk = 0; tk < 8; ++tk) { const int task = tid + 512 * tk, d = task & 255, i0 = (task >> 8) * 8;
;                                 float e[8];
; #pragma unroll
;                                 for (int q = 0; q < 8; ++q) e[q] = bf2f(ks[(i0 + q) * 264 + d]) * __expf(lg * (float)(127 - i0 - q));
;                                 u32x4 w; w.x = pk2(e[0], e[1]); w.y = pk2(e[2], e[3]); w.z = pk2(e[4], e[5]); w.w = pk2(e[6], e[7]);
;                                 *(u32x4*)(KDT + (size_t)item * 32768 + d * 128 + i0) = w; }
;                             { const int ti = wave;
; #pragma unroll 2
;                               for (int tj = 0; tj < 8; ++tj) {
;                                   f32x4 acc = {0.f, 0.f, 0.f, 0.f};
;                                   if (tj <= ti) {
;                                       const bf16* Qb = qs + (ti * 16 + r16) * 264 + g4 * 8; const bf16* Kb2 = ks + (tj * 16 + r16) * 264 + g4 * 8;
; #pragma unroll
;                                       for (int k0 = 0; k0 < 256; k0 += 32) acc = MFMA16(*(const bf16x8*)(Kb2 + k0), *(const bf16x8*)(Qb + k0), acc);
.LBB0_451:
	v_add_u32_e32 v40, s1, v7
	v_ashrrev_i32_e32 v3, 5, v40
	v_and_b32_e32 v2, -8, v3
	v_mad_u64_u32 v[28:29], s[8:9], v2, s71, v[6:7]
	v_sub_u32_e32 v29, 0x7f, v2
	v_cvt_f32_i32_e32 v29, v29
	v_or_b32_e32 v3, 7, v3
	v_mad_u64_u32 v[38:39], s[8:9], v3, s71, v[6:7]
	v_mul_f32_e32 v29, v79, v29
	v_mul_f32_e32 v29, 0x3fb8aa3b, v29
	v_exp_f32_e32 v30, v29
	v_or_b32_e32 v29, 1, v2
	v_sub_u32_e32 v29, 0x7f, v29
	v_cvt_f32_i32_e32 v29, v29
	v_sub_u32_e32 v3, 0x7f, v3
	v_cvt_f32_i32_e32 v3, v3
	s_addk_i32 s1, 0x400
	v_mul_f32_e32 v29, v79, v29
	v_mul_f32_e32 v29, 0x3fb8aa3b, v29
	v_exp_f32_e32 v31, v29
	ds_read_u16 v29, v28
	ds_read_u16 v32, v28 offset:528
	v_mul_f32_e32 v3, v79, v3
	v_mul_f32_e32 v3, 0x3fb8aa3b, v3
	s_cmpk_eq_i32 s1, 0x1000
	s_waitcnt lgkmcnt(0)
	v_lshlrev_b32_e32 v33, 16, v32
	v_lshlrev_b32_e32 v32, 16, v29
	v_or_b32_e32 v29, 2, v2
	v_sub_u32_e32 v29, 0x7f, v29
	v_cvt_f32_i32_e32 v29, v29
	v_pk_mul_f32 v[30:31], v[30:31], v[32:33]
	v_mul_f32_e32 v29, v79, v29
	v_mul_f32_e32 v29, 0x3fb8aa3b, v29
	v_exp_f32_e32 v32, v29
	v_or_b32_e32 v29, 3, v2
	v_sub_u32_e32 v29, 0x7f, v29
	v_cvt_f32_i32_e32 v29, v29
	v_mul_f32_e32 v29, v79, v29
	v_mul_f32_e32 v29, 0x3fb8aa3b, v29
	v_exp_f32_e32 v33, v29
	ds_read_u16 v29, v28 offset:1056
	ds_read_u16 v34, v28 offset:1584
	s_waitcnt lgkmcnt(0)
	v_lshlrev_b32_e32 v35, 16, v34
	v_lshlrev_b32_e32 v34, 16, v29
	v_or_b32_e32 v29, 4, v2
	v_sub_u32_e32 v29, 0x7f, v29
	v_cvt_f32_i32_e32 v29, v29
	v_pk_mul_f32 v[32:33], v[32:33], v[34:35]
	v_mul_f32_e32 v29, v79, v29
	v_mul_f32_e32 v29, 0x3fb8aa3b, v29
	v_exp_f32_e32 v34, v29
	v_or_b32_e32 v29, 5, v2
	v_sub_u32_e32 v29, 0x7f, v29
	v_cvt_f32_i32_e32 v29, v29
	v_mul_f32_e32 v29, v79, v29
	v_mul_f32_e32 v29, 0x3fb8aa3b, v29
	v_exp_f32_e32 v35, v29
	ds_read_u16 v29, v28 offset:2112
	ds_read_u16 v36, v28 offset:2640
	s_waitcnt lgkmcnt(0)
	v_lshlrev_b32_e32 v37, 16, v36
	v_lshlrev_b32_e32 v36, 16, v29
	v_or_b32_e32 v29, 6, v2
	v_sub_u32_e32 v29, 0x7f, v29
	v_cvt_f32_i32_e32 v29, v29
	v_pk_mul_f32 v[34:35], v[34:35], v[36:37]
	v_exp_f32_e32 v37, v3
	ds_read_u16 v3, v28 offset:3168
	ds_read_u16 v28, v38
	v_mul_f32_e32 v29, v79, v29
	v_mul_f32_e32 v29, 0x3fb8aa3b, v29
	v_exp_f32_e32 v36, v29
	s_waitcnt lgkmcnt(0)
	v_lshlrev_b32_e32 v29, 16, v28
	v_lshlrev_b32_e32 v28, 16, v3
	v_pk_mul_f32 v[36:37], v[36:37], v[28:29]
	v_ashrrev_i32_e32 v3, 31, v2
	v_cvt_pk_bf16_f32 v28, v30, v31
	v_cvt_pk_bf16_f32 v29, v32, v33
	v_cvt_pk_bf16_f32 v30, v34, v35
	v_cvt_pk_bf16_f32 v31, v36, v37
	v_lshlrev_b32_e32 v2, 4, v2
	v_lshl_add_u64 v[2:3], v[2:3], 1, v[0:1]
	global_store_dwordx4 v[2:3], v[28:31], off
	v_add_u32_e32 v2, 0x200, v40
	v_ashrrev_i32_e32 v3, 5, v2
	v_and_b32_e32 v2, -8, v3
	v_mad_u64_u32 v[28:29], s[8:9], v2, s71, v[6:7]
	v_sub_u32_e32 v29, 0x7f, v2
	v_cvt_f32_i32_e32 v29, v29
	v_or_b32_e32 v3, 7, v3
	v_mad_u64_u32 v[38:39], s[8:9], v3, s71, v[6:7]
	v_mul_f32_e32 v29, v79, v29
	v_mul_f32_e32 v29, 0x3fb8aa3b, v29
	v_exp_f32_e32 v30, v29
	v_or_b32_e32 v29, 1, v2
	v_sub_u32_e32 v29, 0x7f, v29
	v_cvt_f32_i32_e32 v29, v29
	v_sub_u32_e32 v3, 0x7f, v3
	v_cvt_f32_i32_e32 v3, v3
	v_mul_f32_e32 v29, v79, v29
	v_mul_f32_e32 v29, 0x3fb8aa3b, v29
	v_exp_f32_e32 v31, v29
	ds_read_u16 v29, v28
	ds_read_u16 v32, v28 offset:528
	v_mul_f32_e32 v3, v79, v3
	v_mul_f32_e32 v3, 0x3fb8aa3b, v3
	s_waitcnt lgkmcnt(0)
	v_lshlrev_b32_e32 v33, 16, v32
	v_lshlrev_b32_e32 v32, 16, v29
	v_or_b32_e32 v29, 2, v2
	v_sub_u32_e32 v29, 0x7f, v29
	v_cvt_f32_i32_e32 v29, v29
	v_pk_mul_f32 v[30:31], v[30:31], v[32:33]
	v_mul_f32_e32 v29, v79, v29
	v_mul_f32_e32 v29, 0x3fb8aa3b, v29
	v_exp_f32_e32 v32, v29
	v_or_b32_e32 v29, 3, v2
	v_sub_u32_e32 v29, 0x7f, v29
	v_cvt_f32_i32_e32 v29, v29
	v_mul_f32_e32 v29, v79, v29
	v_mul_f32_e32 v29, 0x3fb8aa3b, v29
	v_exp_f32_e32 v33, v29
	ds_read_u16 v29, v28 offset:1056
	ds_read_u16 v34, v28 offset:1584
	s_waitcnt lgkmcnt(0)
	v_lshlrev_b32_e32 v35, 16, v34
	v_lshlrev_b32_e32 v34, 16, v29
	v_or_b32_e32 v29, 4, v2
	v_sub_u32_e32 v29, 0x7f, v29
	v_cvt_f32_i32_e32 v29, v29
	v_pk_mul_f32 v[32:33], v[32:33], v[34:35]
	v_mul_f32_e32 v29, v79, v29
	v_mul_f32_e32 v29, 0x3fb8aa3b, v29
	v_exp_f32_e32 v34, v29
	v_or_b32_e32 v29, 5, v2
	v_sub_u32_e32 v29, 0x7f, v29
	v_cvt_f32_i32_e32 v29, v29
	v_mul_f32_e32 v29, v79, v29
	v_mul_f32_e32 v29, 0x3fb8aa3b, v29
	v_exp_f32_e32 v35, v29
	ds_read_u16 v29, v28 offset:2112
	ds_read_u16 v36, v28 offset:2640
	s_waitcnt lgkmcnt(0)
	v_lshlrev_b32_e32 v37, 16, v36
	v_lshlrev_b32_e32 v36, 16, v29
	v_or_b32_e32 v29, 6, v2
	v_sub_u32_e32 v29, 0x7f, v29
	v_cvt_f32_i32_e32 v29, v29
	v_pk_mul_f32 v[34:35], v[34:35], v[36:37]
	v_exp_f32_e32 v37, v3
	ds_read_u16 v3, v28 offset:3168
	ds_read_u16 v28, v38
	v_mul_f32_e32 v29, v79, v29
	v_mul_f32_e32 v29, 0x3fb8aa3b, v29
	v_exp_f32_e32 v36, v29
	s_waitcnt lgkmcnt(0)
	v_lshlrev_b32_e32 v29, 16, v28
	v_lshlrev_b32_e32 v28, 16, v3
	v_pk_mul_f32 v[36:37], v[36:37], v[28:29]
	v_ashrrev_i32_e32 v3, 31, v2
	v_cvt_pk_bf16_f32 v28, v30, v31
	v_cvt_pk_bf16_f32 v29, v32, v33
	v_cvt_pk_bf16_f32 v30, v34, v35
	v_cvt_pk_bf16_f32 v31, v36, v37
	v_lshlrev_b32_e32 v2, 4, v2
	v_lshl_add_u64 v[2:3], v[2:3], 1, v[0:1]
	global_store_dwordx4 v[2:3], v[28:31], off
	s_cbranch_scc0 .LBB0_451
	s_and_b32 s1, s7, 3
	s_add_i32 s3, s3, s2
	s_lshl_b32 s1, s1, 9
	v_and_b32_e32 v0, 0x70, v73
	v_add_u32_e32 v0, s3, v0
	v_mov_b32_e32 v196, s1
	v_mad_i64_i32 v[0:1], s[2:3], v0, s69, v[196:197]
	v_lshl_add_u64 v[28:29], v[184:185], 0, v[0:1]
	s_mov_b32 s1, 0
	v_mov_b32_e32 v30, v78
	v_mov_b32_e32 v31, v77
	s_mov_b32 s7, 0
	ds_read_b128 v[128:131], v74
	ds_read_b128 v[132:135], v74 offset:64
	ds_read_b128 v[136:139], v74 offset:128
	ds_read_b128 v[140:143], v74 offset:192
	ds_read_b128 v[144:147], v74 offset:256
	ds_read_b128 v[160:163], v74 offset:320
	ds_read_b128 v[164:167], v74 offset:384
	ds_read_b128 v[168:171], v74 offset:448
	s_branch .LBB0_454

; #define MFMA16(a, b, c) __builtin_amdgcn_mfma_f32_16x16x32_bf16((a), (b), (c), 0, 0, 0)
; __global__ void __launch_bounds__(512, 2) fwd_megakernel(Params kp_) {
;     ...
;                               for (int tj = 0; tj < 8; ++tj) {
;                                   f32x4 acc = {0.f, 0.f, 0.f, 0.f};
;                                   if (tj <= ti) {
;                                       const bf16* Qb = qs + (ti * 16 + r16) * 264 + g4 * 8; const bf16* Kb2 = ks + (tj * 16 + r16) * 264 + g4 * 8;
; #pragma unroll
;                                       for (int k0 = 0; k0 < 256; k0 += 32) acc = MFMA16(*(const bf16x8*)(Kb2 + k0), *(const bf16x8*)(Qb + k0), acc);
;                                   }
.LBB0_454:
	v_mov_b32_e32 v33, 0
	s_cmp_gt_i32 s7, s4
	v_add_u32_e32 v32, s1, v76
	v_mov_b32_e32 v0, 0
	v_mov_b32_e32 v1, 0
	v_mov_b32_e32 v2, 0
	v_mov_b32_e32 v3, 0
	s_cbranch_scc1 .LBB0_456
	v_add_u32_e32 v0, 0x10800, v32
	ds_read_b128 v[96:99], v0
	ds_read_b128 v[100:103], v0 offset:64
	ds_read_b128 v[104:107], v0 offset:128
	ds_read_b128 v[108:111], v0 offset:192
	ds_read_b128 v[112:115], v0 offset:256
	ds_read_b128 v[116:119], v0 offset:320
	ds_read_b128 v[120:123], v0 offset:384
	ds_read_b128 v[124:127], v0 offset:448
	s_waitcnt lgkmcnt(0)
	v_mfma_f32_16x16x32_bf16 v[0:3], v[96:99], v[128:131], 0
	v_mfma_f32_16x16x32_bf16 v[0:3], v[100:103], v[132:135], v[0:3]
	v_mfma_f32_16x16x32_bf16 v[0:3], v[104:107], v[136:139], v[0:3]
	v_mfma_f32_16x16x32_bf16 v[0:3], v[108:111], v[140:143], v[0:3]
	v_mfma_f32_16x16x32_bf16 v[0:3], v[112:115], v[144:147], v[0:3]
	v_mfma_f32_16x16x32_bf16 v[0:3], v[116:119], v[160:163], v[0:3]
	v_mfma_f32_16x16x32_bf16 v[0:3], v[120:123], v[164:167], v[0:3]
	v_mfma_f32_16x16x32_bf16 v[0:3], v[124:127], v[168:171], v[0:3]

; __device__ __forceinline__ unsigned pk2(float lo, float hi) { const f32x2_t v = {lo, hi}; const bf16x2_t b = __builtin_convertvector(v, bf16x2_t); return __builtin_bit_cast(unsigned, b); }
; #define MFMA16(a, b, c) __builtin_amdgcn_mfma_f32_16x16x32_bf16((a), (b), (c), 0, 0, 0)
; __global__ void __launch_bounds__(512, 2) fwd_megakernel(Params kp_) {
;     ...
;                               for (int tj = 0; tj < 8; ++tj) {
;                                   f32x4 acc = {0.f, 0.f, 0.f, 0.f};
;                                   if (tj <= ti) {
;                                       const bf16* Qb = qs + (ti * 16 + r16) * 264 + g4 * 8; const bf16* Kb2 = ks + (tj * 16 + r16) * 264 + g4 * 8;
; #pragma unroll
;                                       for (int k0 = 0; k0 < 256; k0 += 32) acc = MFMA16(*(const bf16x8*)(Kb2 + k0), *(const bf16x8*)(Qb + k0), acc);
;                                   }
;                                   const int i = ti * 16 + r16; float v4[4];
; #pragma unroll
;                                   for (int j = 0; j < 4; ++j) { const int jj = tj * 16 + g4 * 4 + j; v4[j] = (i >= jj) ? acc[j] * __expf(lg * (float)(i - jj)) : 0.f; }
;                                   bf16* ap = (rep_ + 1 < REP_R1) ? (dmy + i * 256 + tj * 16 + g4 * 4) : (proj + (size_t)(row0 + i) * RETP + 1024 + h * 256 + tj * 16 + g4 * 4);
;                                   u32x2 w; w.x = pk2(v4[0], v4[1]); w.y = pk2(v4[2], v4[3]); *(u32x2*)ap = w;
.LBB0_464:
	s_or_b64 exec, exec, s[2:3]
	v_cvt_pk_bf16_f32 v2, v33, v35
	v_cvt_pk_bf16_f32 v3, v34, v1
	global_store_dwordx2 v[28:29], v[2:3], off
	s_cmp_ge_i32 s7, s4
	v_mov_b32_e32 v1, 0
	v_mov_b32_e32 v2, 0
	v_mov_b32_e32 v3, 0
	s_cbranch_scc1 .LBB0_466
	v_add_u32_e32 v33, 0x12900, v32
	ds_read_b128 v[96:99], v33
	ds_read_b128 v[100:103], v33 offset:64
	ds_read_b128 v[104:107], v33 offset:128
	ds_read_b128 v[108:111], v33 offset:192
	ds_read_b128 v[112:115], v33 offset:256
	ds_read_b128 v[116:119], v33 offset:320
	ds_read_b128 v[120:123], v33 offset:384
	ds_read_b128 v[124:127], v33 offset:448
	s_waitcnt lgkmcnt(0)
	v_mfma_f32_16x16x32_bf16 v[0:3], v[96:99], v[128:131], 0
	v_mfma_f32_16x16x32_bf16 v[0:3], v[100:103], v[132:135], v[0:3]
	v_mfma_f32_16x16x32_bf16 v[0:3], v[104:107], v[136:139], v[0:3]
	v_mfma_f32_16x16x32_bf16 v[0:3], v[108:111], v[140:143], v[0:3]
	v_mfma_f32_16x16x32_bf16 v[0:3], v[112:115], v[144:147], v[0:3]
	v_mfma_f32_16x16x32_bf16 v[0:3], v[116:119], v[160:163], v[0:3]
	v_mfma_f32_16x16x32_bf16 v[0:3], v[120:123], v[164:167], v[0:3]
	v_mfma_f32_16x16x32_bf16 v[0:3], v[124:127], v[168:171], v[0:3]

; __global__ void __launch_bounds__(512, 2) fwd_megakernel(Params kp_) {
;     ...
;                             if (tid < 384) {
;                                 const int cg = tid % 48, rg = tid / 48, part = cg >> 4, d = (cg & 15) * 8, ch = part * 512 + h * 128 + d;
;                                 u32x4 raw[11];
; #pragma unroll
;                                 for (int rr = 0; rr < 11; ++rr) { const int i = rg * 8 - 3 + rr;
;                                     raw[rr] = (tpos0 + i >= 0) ? *(const u32x4*)(proj + (size_t)(row0 + i) * HYBN + ch) : (u32x4){0u, 0u, 0u, 0u}; }
;                                 f32x4 wa[4], wb[4];
; #pragma unroll
;                                 for (int j = 0; j < 4; ++j) { wa[j] = *(const f32x4*)(convw + j * 1536 + ch); wb[j] = *(const f32x4*)(convw + j * 1536 + ch + 4); }
;                                 float* dst = (part == 0 ? qc : (part == 1 ? kc : vc)) + d;
; #pragma unroll
;                                 for (int r8 = 0; r8 < 8; ++r8) {
;                                     f32x4 a0 = {0.f, 0.f, 0.f, 0.f}, a1 = {0.f, 0.f, 0.f, 0.f};
; #pragma unroll
;                                     for (int j = 0; j < 4; ++j) { const u32x4 x = raw[r8 + j];
;                                         a0 += (f32x4){bflo(x.x), bfhi(x.x), bflo(x.y), bfhi(x.y)} * wa[j]; a1 += (f32x4){bflo(x.z), bfhi(x.z), bflo(x.w), bfhi(x.w)} * wb[j]; }
;                                     const int i = rg * 8 + r8;
;                                     *(f32x4*)(dst + i * 128) = (f32x4){siluf(a0.x), siluf(a0.y), siluf(a0.z), siluf(a0.w)};
;                                     *(f32x4*)(dst + i * 128 + 4) = (f32x4){siluf(a1.x), siluf(a1.y), siluf(a1.z), siluf(a1.w)};
;                                 }
;                             }
;                             if (wave == 7) {
;                                 const float ga = gab[(size_t)(row0 + lane) * 8 + h], gb = gab[(size_t)(row0 + lane) * 8 + 4 + h];
;                                 float gv = -__expf(p.a_log[li * 4 + h]) * softplusf(ga + p.dt_bias[li * 4 + h]);
; #pragma unroll
;                                 for (int o = 1; o < 64; o <<= 1) { const float t = SHU(gv, o); if (lane >= o) gv += t; }
;                                 { int l2 = lane; asm volatile("" : "+v"(l2)); gc[l2] = gv; bet[l2] = __builtin_amdgcn_rcpf(1.f + __expf(-gb)); }
;                             }
.LBB0_668:
	s_and_b64 vcc, exec, s[0:1]
	s_cbranch_vccz .LBB0_1005
	v_readlane_b32 s0, v253, 16
	v_mov_b32_e32 v0, v199
	v_readlane_b32 s1, v253, 17
	s_andn2_b64 vcc, exec, s[0:1]
	v_readfirstlane_b32 s3, v0
	s_cbranch_vccnz .LBB0_791
	s_movk_i32 s1, 0x180
	v_cmp_gt_i32_e64 s[36:37], s1, v0
	s_mov_b32 s1, 0x2aaaaaab
	v_mul_hi_i32 v1, v0, s1
	v_lshrrev_b32_e32 v2, 31, v1
	v_ashrrev_i32_e32 v1, 3, v1
	v_add_u32_e32 v1, v1, v2
	v_mul_lo_u32 v2, v1, 48
	s_ashr_i32 s0, s3, 6
	v_sub_u32_e32 v2, v0, v2
	s_add_i32 s1, 0, 0x8000
	s_add_i32 s4, 0, 0x10000
	v_lshlrev_b32_e32 v3, 3, v2
	s_cmp_eq_u32 s0, 7
	v_and_b32_e32 v6, 0x78, v3
	v_mov_b32_e32 v3, s1
	s_cselect_b64 s[38:39], -1, 0
	s_lshl_b32 s30, s0, 10
	s_lshl_b32 s1, s0, 3
	s_lshr_b32 s100, s0, 1
	s_lshl_b32 s100, s100, 11
	s_and_b32 s101, s0, 1
	s_lshl_b32 s101, s101, 8
	s_or_b32 s100, s100, s101
	s_mov_b32 s101, 0
	v_and_b32_e32 v98, 63, v0
	v_readlane_b32 s6, v253, 12
	s_cmpk_gt_u32 s3, 0xff
	v_and_b32_e32 v76, 0x18, v98
	v_and_b32_e32 v196, 0x27, v98
	v_lshlrev_b32_e32 v196, 1, v196
	v_lshl_or_b32 v196, v76, 7, v196
	v_readlane_b32 s7, v253, 13
	s_cselect_b64 s[34:35], -1, 0
	s_add_i32 s2, 0, 0x18000
	s_waitcnt vmcnt(1)
	v_lshl_add_u64 v[76:77], s[6:7], 0, v[196:197]
	s_cmpk_lt_u32 s3, 0x100
	v_readlane_b32 s6, v254, 29
	s_cselect_b32 s3, s6, s2
	s_lshl_b32 s5, s0, 4
	v_and_b32_e32 v99, 15, v0
	s_and_b32 s5, s5, 48
	v_cmp_eq_u32_e64 s[8:9], 0, v98
	v_ashrrev_i32_e32 v5, 4, v2
	v_lshlrev_b32_e32 v100, 3, v1
	v_lshlrev_b32_e32 v8, 12, v1
	v_or_b32_e32 v1, s5, v99
	v_writelane_b32 v255, s8, 30
	v_cmp_eq_u32_e32 vcc, 1, v5
	v_mul_u32_u24_e32 v1, 0x110, v1
	v_and_b32_e32 v13, 48, v0
	v_writelane_b32 v255, s9, 31
	v_cmp_gt_u32_e64 s[8:9], 2, v98
	v_cndmask_b32_e64 v3, v3, 0, vcc
	v_mov_b32_e32 v7, s4
	v_cmp_gt_u32_e32 vcc, 16, v2
	v_add3_u32 v102, s3, v1, v13
	s_movk_i32 s3, 0xff
	v_and_b32_e32 v1, 0x7f, v0
	v_lshrrev_b32_e32 v14, 2, v0
	v_writelane_b32 v255, s8, 32
	v_cndmask_b32_e32 v2, v3, v7, vcc
	v_cmp_lt_i32_e64 s[42:43], s3, v0
	v_bfe_u32 v196, v1, 4, 3
	v_lshlrev_b32_e32 v196, 7, v196
	v_and_or_b32 v196, v1, 15, v196
	v_lshlrev_b32_e32 v196, 4, v196
	v_and_b32_e32 v14, 32, v14
	s_movk_i32 s3, 0x7f
	v_writelane_b32 v255, s9, 33
	v_cmp_gt_u32_e64 s[8:9], 4, v98
	v_lshl_add_u32 v7, v6, 2, v2
	v_lshl_add_u64 v[2:3], s[92:93], 0, v[196:197]
	v_lshlrev_b32_e32 v196, 5, v14
	v_lshl_add_u32 v15, v1, 1, s6
	v_cmp_lt_i32_e64 s[10:11], s3, v0
	v_lshl_add_u32 v1, v0, 2, 0
	s_movk_i32 s3, 0x80
	v_writelane_b32 v255, s8, 34
	v_lshl_add_u64 v[78:79], v[2:3], 0, v[196:197]
	v_add_u32_e32 v2, 0x8000, v1
	v_add_u32_e32 v1, 0xfffffe00, v1
	v_cmp_gt_i32_e64 s[12:13], s3, v0
	v_writelane_b32 v255, s9, 35
	v_cmp_gt_u32_e64 s[8:9], 8, v98
	v_mov_b32_e32 v3, 0x1a800000
	v_mov_b32_e32 v16, 0x18800000
	v_cndmask_b32_e64 v104, v1, v2, s[12:13]
	v_add_u32_e32 v1, 0xffffff80, v0
	v_writelane_b32 v255, s8, 36
	v_bfe_u32 v4, v0, 4, 2
	v_cmp_eq_u32_e64 s[40:41], 0, v0
	v_cndmask_b32_e64 v196, v3, v16, s[12:13]
	v_cndmask_b32_e64 v0, v1, v0, s[12:13]
	v_writelane_b32 v255, s9, 37
	v_cmp_gt_u32_e64 s[8:9], 16, v98
	v_or_b32_e32 v9, s30, v98
	v_lshl_add_u64 v[2:3], s[86:87], 0, v[196:197]
	v_ashrrev_i32_e32 v1, 31, v0
	v_writelane_b32 v255, s8, 38
	s_lshl_b32 s3, s0, 5
	v_readlane_b32 s7, v254, 30
	v_or_b32_e32 v10, 64, v98
	v_and_b32_e32 v80, 0x18, v0
	v_and_b32_e32 v81, 0x67, v0
	v_lshlrev_b32_e32 v81, 1, v81
	v_lshl_or_b32 v80, v80, 7, v81
	v_mov_b32_e32 v81, 0
	v_lshl_add_u64 v[80:81], v[2:3], 0, v[80:81]
	v_writelane_b32 v255, s9, 39
	v_cmp_gt_u32_e64 s[8:9], 32, v98
	v_lshlrev_b32_e32 v0, 2, v9
	s_add_i32 s44, s7, s3
	s_mul_i32 s3, s0, 0x440
	v_lshlrev_b32_e32 v11, 2, v98
	v_writelane_b32 v255, s8, 40
	v_add_u32_e32 v120, s4, v0
	v_add_u32_e32 v122, 0, v0
	v_or_b32_e32 v0, s3, v98
	v_add_lshl_u32 v1, v10, s3, 1
	s_or_b32 s3, s1, 1
	v_add_u32_e32 v12, 0, v11
	v_writelane_b32 v255, s9, 41
	s_lshl_b32 s4, s3, 2
	s_add_i32 s8, s100, 8
	s_add_i32 s45, s7, s4
	s_mul_i32 s4, s3, 0x88
	v_lshl_add_u32 v152, s3, 9, v12
	s_ashr_i32 s9, s8, 31
	s_or_b32 s3, s1, 2
	v_lshl_or_b32 v103, v4, 2, s5
	v_writelane_b32 v255, s8, 42
	s_lshl_b32 s5, s3, 2
	v_lshlrev_b32_e32 v0, 1, v0
	v_writelane_b32 v255, s9, 43
	s_add_i32 s5, s7, s5
	s_add_i32 s8, s100, 16
	v_add_u32_e32 v143, s2, v0
	v_add_u32_e32 v144, s2, v1
	v_add_u32_e32 v145, s6, v0
	v_add_u32_e32 v146, s6, v1
	v_add_lshl_u32 v0, s4, v98, 1
	v_add_lshl_u32 v1, v10, s4, 1
	v_writelane_b32 v255, s5, 44
	s_add_i32 s5, s4, 0x88
	v_lshl_add_u32 v157, s3, 9, v12
	s_ashr_i32 s9, s8, 31
	s_or_b32 s3, s1, 3
	v_add_u32_e32 v148, s2, v0
	v_add_u32_e32 v149, s2, v1
	v_add_u32_e32 v150, s6, v0
	v_add_u32_e32 v151, s6, v1
	v_add_lshl_u32 v0, s5, v98, 1
	v_add_lshl_u32 v1, v10, s5, 1
	v_writelane_b32 v255, s8, 45
	s_lshl_b32 s5, s3, 2
	s_add_i32 s5, s7, s5
	v_writelane_b32 v255, s9, 46
	s_add_i32 s8, s100, 24
	v_writelane_b32 v255, s5, 47
; __device__ __forceinline__ unsigned f2bf(float f) { return pk2(f, 0.f) & 0xffffu; }
; __global__ void __launch_bounds__(512, 2) fwd_megakernel(Params kp_) {
;     ...
;                                     for (int ii = 0; ii < 8; ++ii) { const int i = wave * 8 + ii;
;                                         const float rq = rsqrtf(sq[ii] + EPS) * 0.08838834764831845f, rk = rsqrtf(sk[ii] + EPS);
;                                         const float eg = __expf(gc[i]);
;                                         const float qn0 = q0[ii] * rq, qn1 = q1[ii] * rq, kn0 = k0[ii] * rk, kn1 = k1[ii] * rk;
;                                         qbf[i * 136 + lane] = (bf16)f2bf(qn0); qbf[i * 136 + 64 + lane] = (bf16)f2bf(qn1);
;                                         kbf[i * 136 + lane] = (bf16)f2bf(kn0); kbf[i * 136 + 64 + lane] = (bf16)f2bf(kn1);
;                                         kc[i * 128 + lane] = kn0; kc[i * 128 + 64 + lane] = kn1;
;                                         bf16* qd = QDbuf + (size_t)item * 8192 + i * 128; qd[lane] = (bf16)f2bf(qn0 * eg); qd[64 + lane] = (bf16)f2bf(qn1 * eg);
;                                     }
;                                 }
;                                 if (tid == 0) gle[item] = __expf(gl);
;                             }
;                             LBAR();
;                             {
;                                 float* Ls = qc;
; #pragma unroll 2
;                                 for (int q4 = 0; q4 < 4; ++q4) { const int idx = wave * 4 + q4, kind = idx >> 4, ti = (idx >> 2) & 3, tj = idx & 3;
;                                     const bf16* Ab = (kind == 0 ? kbf : qbf) + (ti * 16 + r16) * 136 + g4 * 8; const bf16* Bb = kbf + (tj * 16 + r16) * 136 + g4 * 8;
;                                     f32x4 acc = {0.f, 0.f, 0.f, 0.f};
; #pragma unroll
;                                     for (int k0 = 0; k0 < 128; k0 += 32) acc = MFMA16(*(const bf16x8*)(Ab + k0), *(const bf16x8*)(Bb + k0), acc);
;                                     const int jj = tj * 16 + r16; const float gj = gc[jj];
; #pragma unroll
;                                     for (int j = 0; j < 4; ++j) { const int i = ti * 16 + g4 * 4 + j; const float dec = __expf(fminf(gc[i] - gj, 0.f));
;                                         if (kind == 0) Ls[i * 64 + jj] = (i > jj) ? acc[j] * bet[i] * dec : 0.f;
	s_add_i32 s5, s4, 0x110
	v_lshl_add_u32 v162, s3, 9, v12
	s_ashr_i32 s9, s8, 31
	s_or_b32 s3, s1, 4
	v_add_u32_e32 v153, s2, v0
	v_add_u32_e32 v154, s2, v1
	v_add_u32_e32 v155, s6, v0
	v_add_u32_e32 v156, s6, v1
	v_add_lshl_u32 v0, s5, v98, 1
	v_add_lshl_u32 v1, v10, s5, 1
	v_writelane_b32 v255, s8, 48
	s_lshl_b32 s5, s3, 2
	s_add_i32 s5, s7, s5
	v_writelane_b32 v255, s9, 49
	s_add_i32 s8, s100, 128
	v_writelane_b32 v255, s5, 50
	s_add_i32 s5, s4, 0x198
	v_lshl_add_u32 v167, s3, 9, v12
	s_ashr_i32 s9, s8, 31
	s_or_b32 s3, s1, 5
	v_add_u32_e32 v158, s2, v0
	v_add_u32_e32 v159, s2, v1
	v_add_u32_e32 v160, s6, v0
	v_add_u32_e32 v161, s6, v1
	v_add_lshl_u32 v0, s5, v98, 1
	v_add_lshl_u32 v1, v10, s5, 1
	v_writelane_b32 v255, s8, 51
	s_lshl_b32 s5, s3, 2
	s_add_i32 s5, s7, s5
	v_writelane_b32 v255, s9, 52
	s_add_i32 s8, s100, 136
	v_writelane_b32 v255, s5, 53
	s_add_i32 s5, s4, 0x220
	v_lshl_add_u32 v172, s3, 9, v12
	s_ashr_i32 s9, s8, 31
	s_or_b32 s3, s1, 6
	v_add_u32_e32 v163, s2, v0
	v_add_u32_e32 v164, s2, v1
	v_add_u32_e32 v165, s6, v0
	v_add_u32_e32 v166, s6, v1
	v_add_lshl_u32 v0, s5, v98, 1
	v_add_lshl_u32 v1, v10, s5, 1
	v_writelane_b32 v255, s8, 54
	s_lshl_b32 s5, s3, 2
	s_add_i32 s5, s7, s5
	v_writelane_b32 v255, s9, 55
	v_writelane_b32 v255, s5, 56
	s_add_i32 s5, s4, 0x2a8
	v_add_u32_e32 v168, s2, v0
	v_add_u32_e32 v170, s6, v0
	v_add_lshl_u32 v0, s5, v98, 1
	s_addk_i32 s4, 0x330
	v_add_u32_e32 v173, s2, v0
	v_add_u32_e32 v175, s6, v0
	s_or_b32 s1, s1, 7
	v_add_lshl_u32 v0, s4, v98, 1
	s_add_i32 s14, s100, 0x90
	v_lshl_add_u32 v177, s3, 9, v12
	s_lshl_b32 s3, s1, 2
	v_add_u32_e32 v178, s2, v0
	v_add_u32_e32 v180, s6, v0
	s_add_i32 s16, s100, 0x98
	v_lshl_add_u32 v182, s1, 9, v12
	v_lshlrev_b32_e32 v0, 2, v103
	v_readlane_b32 s1, v254, 31
	v_or_b32_e32 v185, 1, v103
	v_add_u32_e32 v183, s7, v0
	v_add_u32_e32 v184, s1, v0
	v_lshlrev_b32_e32 v0, 2, v185
	v_or_b32_e32 v188, 2, v103
	v_add_u32_e32 v169, s2, v1
	v_add_u32_e32 v171, s6, v1
	v_add_lshl_u32 v1, v10, s5, 1
	v_add_u32_e32 v186, s7, v0
	v_add_u32_e32 v187, s1, v0
	v_lshlrev_b32_e32 v0, 2, v188
	v_or_b32_e32 v191, 3, v103
	v_lshl_add_u32 v147, s0, 12, v12
	v_add_u32_e32 v174, s2, v1
	v_add_u32_e32 v176, s6, v1
	v_add_lshl_u32 v1, v10, s4, 1
	v_add_u32_e32 v189, s7, v0
	v_add_u32_e32 v190, s1, v0
	v_lshlrev_b32_e32 v0, 2, v191
	s_and_b32 s0, s0, 3
	v_add_u32_e32 v179, s2, v1
	v_add_u32_e32 v181, s6, v1
	v_add_u32_e32 v193, s1, v0
	s_lshl_b32 s1, s0, 12
	v_lshlrev_b32_e32 v1, 10, v4
	v_lshlrev_b32_e32 v211, 2, v99
	v_or3_b32 v212, s1, v1, v211
	s_movk_i32 s1, 0x110
	v_lshlrev_b32_e32 v1, 6, v4
	s_lshl_b32 s0, s0, 11
	v_bfe_u32 v196, v99, 3, 1
	v_and_b32_e32 v2, 7, v99
	v_lshlrev_b32_e32 v2, 1, v2
	v_lshl_or_b32 v2, v196, 8, v2
	v_mad_u32_u24 v213, v99, s1, v13
	v_or3_b32 v196, s0, v1, v2
	v_readlane_b32 s0, v254, 20
	v_readlane_b32 s1, v254, 21
	s_add_i32 s3, s7, s3
	v_add_u32_e32 v192, s7, v0
	v_lshl_add_u64 v[82:83], s[0:1], 0, v[196:197]
	v_readlane_b32 s0, v254, 22
	v_mul_u32_u24_e32 v0, 0x110, v14
	v_lshl_add_u32 v194, v14, 2, s7
	v_and_b32_e32 v196, 12, v103
	v_lshl_or_b32 v2, v196, 4, v2
	v_and_b32_e32 v196, 0x30, v103
	v_lshl_or_b32 v196, v196, 7, v2
	v_readlane_b32 s1, v254, 23
	v_add_u32_e32 v101, -3, v100
	v_add_u32_e32 v105, -2, v100
	v_add_u32_e32 v106, -1, v100
	v_or_b32_e32 v107, 1, v100
	v_or_b32_e32 v108, 2, v100
	v_or_b32_e32 v109, 3, v100
	v_or_b32_e32 v110, 4, v100
	v_or_b32_e32 v111, 5, v100
	v_or_b32_e32 v112, 6, v100
	v_or_b32_e32 v113, 7, v100
	v_add_u32_e32 v114, -4, v11
	v_add_u32_e32 v115, -8, v11
	v_add_u32_e32 v116, -16, v11
	v_subrev_u32_e32 v117, 32, v11
	v_subrev_u32_e32 v118, 64, v11
	v_add_u32_e32 v119, 0xffffff80, v11
	v_add_u32_e32 v121, 0x100, v120
	v_add_u32_e32 v123, 0x200, v120
	v_add_u32_e32 v124, 0x300, v120
	v_add_u32_e32 v125, 0x400, v120
	v_add_u32_e32 v126, 0x500, v120
	v_add_u32_e32 v127, 0x600, v120
	v_add_u32_e32 v128, 0x700, v120
	v_add_u32_e32 v129, 0x800, v120
	v_add_u32_e32 v130, 0x900, v120
	v_add_u32_e32 v131, 0xa00, v120
	v_add_u32_e32 v132, 0xb00, v120
	v_add_u32_e32 v133, 0xc00, v120
	v_add_u32_e32 v134, 0xd00, v120
	v_add_u32_e32 v135, 0xe00, v120
	v_add_u32_e32 v136, 0xf00, v120
	v_xor_b32_e32 v137, 4, v11
	v_xor_b32_e32 v138, 8, v11
	v_xor_b32_e32 v139, 16, v11
	v_xor_b32_e32 v140, 32, v11
	v_xor_b32_e32 v141, 64, v11
	v_xor_b32_e32 v142, 0x80, v11
	s_ashr_i32 s31, s30, 31
	s_ashr_i32 s15, s14, 31
	v_writelane_b32 v255, s3, 57
	s_ashr_i32 s17, s16, 31
	v_add_u32_e32 v195, 16, v194
	v_add_u32_e32 v204, 32, v194
	v_add_u32_e32 v205, 48, v194
	v_add_u32_e32 v206, 64, v194
	v_add_u32_e32 v207, 0x50, v194
	v_add_u32_e32 v208, 0x60, v194
	v_add_u32_e32 v209, 0x70, v194
	v_lshl_or_b32 v210, v5, 9, v6
	v_lshl_add_u64 v[84:85], s[0:1], 0, v[196:197]
	v_add_u32_e32 v196, v7, v8
	v_add_u32_e32 v214, v15, v0
	s_mov_b32 s2, s46
	s_branch .LBB0_672

; __device__ __forceinline__ unsigned f2bf(float f) { return pk2(f, 0.f) & 0xffffu; }
; __device__ __forceinline__ float shfl_idx(float v, int src_lane) { return __builtin_bit_cast(float, __builtin_amdgcn_ds_bpermute(src_lane << 2, __builtin_bit_cast(int, v))); }
; #define LBAR() asm volatile("s_waitcnt lgkmcnt(0)\n\ts_barrier" ::: "memory")
; __global__ void __launch_bounds__(512, 2) fwd_megakernel(Params kp_) {
;     ...
;                             LBAR();
;                             {
;                                 const float gl = gc[63];
;                                 {
;                                     float q0[8], q1[8], k0[8], k1[8], sq[8], sk[8];
; #pragma unroll
;                                     for (int ii = 0; ii < 8; ++ii) { const int i = wave * 8 + ii;
;                                         q0[ii] = qc[i * 128 + lane]; q1[ii] = qc[i * 128 + 64 + lane]; k0[ii] = kc[i * 128 + lane]; k1[ii] = kc[i * 128 + 64 + lane];
;                                         sq[ii] = q0[ii] * q0[ii] + q1[ii] * q1[ii]; sk[ii] = k0[ii] * k0[ii] + k1[ii] * k1[ii]; }
; #pragma unroll
;                                     for (int o = 1; o < 64; o <<= 1) {
; #pragma unroll
;                                         for (int ii = 0; ii < 8; ++ii) { sq[ii] += shfl_idx(sq[ii], lane ^ o); sk[ii] += shfl_idx(sk[ii], lane ^ o); } }
; #pragma unroll
;                                     for (int ii = 0; ii < 8; ++ii) { const int i = wave * 8 + ii;
;                                         const float rq = rsqrtf(sq[ii] + EPS) * 0.08838834764831845f, rk = rsqrtf(sk[ii] + EPS);
;                                         const float eg = __expf(gc[i]);
;                                         const float qn0 = q0[ii] * rq, qn1 = q1[ii] * rq, kn0 = k0[ii] * rk, kn1 = k1[ii] * rk;
;                                         qbf[i * 136 + lane] = (bf16)f2bf(qn0); qbf[i * 136 + 64 + lane] = (bf16)f2bf(qn1);
;                                         kbf[i * 136 + lane] = (bf16)f2bf(kn0); kbf[i * 136 + 64 + lane] = (bf16)f2bf(kn1);
;                                         kc[i * 128 + lane] = kn0; kc[i * 128 + 64 + lane] = kn1;
;                                         bf16* qd = QDbuf + (size_t)item * 8192 + i * 128; qd[lane] = (bf16)f2bf(qn0 * eg); qd[64 + lane] = (bf16)f2bf(qn1 * eg);
.LBB0_698:
	v_readlane_b32 s0, v254, 32
	s_waitcnt lgkmcnt(0)
	s_barrier
	ds_read_b32 v54, v120
	ds_read_b32 v55, v121
	v_mov_b32_e32 v0, s0
	ds_read_b32 v62, v0
	ds_read2st64_b32 v[52:53], v122 offset1:1
	s_mov_b32 s4, 0x358637bd
	ds_read_b32 v48, v123
	ds_read_b32 v49, v124
	ds_read2st64_b32 v[46:47], v122 offset0:2 offset1:3
	ds_read_b32 v34, v125
	ds_read_b32 v35, v126
	s_waitcnt lgkmcnt(7)
	v_pk_mul_f32 v[0:1], v[54:55], v[54:55]
	s_waitcnt vmcnt(0) lgkmcnt(3)
	v_pk_mul_f32 v[58:59], v[48:49], v[48:49]
	v_pk_mul_f32 v[2:3], v[52:53], v[52:53]
	v_mov_b32_e32 v5, v0
	v_mov_b32_e32 v4, v2
	v_mov_b32_e32 v0, v3
	v_pk_add_f32 v[0:1], v[4:5], v[0:1]
	ds_bpermute_b32 v3, v137, v1
	ds_bpermute_b32 v2, v137, v0
	s_waitcnt lgkmcnt(4)
	v_pk_mul_f32 v[60:61], v[46:47], v[46:47]
	ds_read2st64_b32 v[36:37], v122 offset0:4 offset1:5
	ds_read_b32 v26, v127
	ds_read_b32 v27, v128
	ds_read2st64_b32 v[28:29], v122 offset0:6 offset1:7
	ds_read_b32 v22, v129
	s_waitcnt lgkmcnt(5)
	v_pk_add_f32 v[0:1], v[0:1], v[2:3]
	ds_bpermute_b32 v3, v138, v1
	ds_bpermute_b32 v2, v138, v0
	ds_read_b32 v23, v130
	ds_read2st64_b32 v[24:25], v122 offset0:8 offset1:9
	ds_read_b32 v14, v131
	ds_read_b32 v15, v132
	ds_read2st64_b32 v[16:17], v122 offset0:10 offset1:11
	ds_read_b32 v8, v133
	ds_read_b32 v9, v134
	ds_read2st64_b32 v[6:7], v122 offset0:12 offset1:13
	s_ashr_i32 s3, s2, 31
	s_waitcnt lgkmcnt(8)
	v_pk_add_f32 v[0:1], v[0:1], v[2:3]
	ds_bpermute_b32 v3, v139, v1
	ds_bpermute_b32 v2, v139, v0
	s_lshl_b64 s[18:19], s[2:3], 14
	v_pk_mul_f32 v[50:51], v[34:35], v[34:35]
	v_pk_mul_f32 v[56:57], v[36:37], v[36:37]
	v_pk_mul_f32 v[42:43], v[26:27], v[26:27]
	s_waitcnt lgkmcnt(0)
	v_pk_add_f32 v[0:1], v[0:1], v[2:3]
	ds_bpermute_b32 v3, v140, v1
	ds_bpermute_b32 v2, v140, v0
	v_pk_mul_f32 v[44:45], v[28:29], v[28:29]
	v_pk_mul_f32 v[38:39], v[22:23], v[22:23]
	v_pk_mul_f32 v[40:41], v[24:25], v[24:25]
	v_pk_mul_f32 v[30:31], v[14:15], v[14:15]
	s_waitcnt lgkmcnt(0)
	v_pk_add_f32 v[4:5], v[0:1], v[2:3]
	ds_bpermute_b32 v11, v141, v5
	ds_bpermute_b32 v10, v141, v4
	ds_read_b32 v0, v135
	ds_read_b32 v1, v136
	ds_read2st64_b32 v[2:3], v122 offset0:14 offset1:15
	v_pk_mul_f32 v[32:33], v[16:17], v[16:17]
	v_pk_mul_f32 v[18:19], v[8:9], v[8:9]
	v_pk_mul_f32 v[20:21], v[6:7], v[6:7]
	s_waitcnt lgkmcnt(3)
	v_pk_add_f32 v[4:5], v[4:5], v[10:11]
	ds_bpermute_b32 v65, v142, v5
	ds_bpermute_b32 v64, v142, v4
	s_waitcnt lgkmcnt(3)
	v_pk_mul_f32 v[10:11], v[0:1], v[0:1]
	s_waitcnt lgkmcnt(2)
	v_pk_mul_f32 v[12:13], v[2:3], v[2:3]
	s_waitcnt lgkmcnt(0)
	v_pk_add_f32 v[4:5], v[4:5], v[64:65]
	s_nop 0
	v_pk_add_f32 v[64:65], v[4:5], s[4:5] op_sel_hi:[1,0]
	s_nop 0
	v_mul_f32_e32 v4, 0x4b800000, v65
	v_cmp_gt_f32_e64 s[0:1], s65, v65
	v_cmp_gt_f32_e32 vcc, s65, v64
	s_nop 0
	v_cndmask_b32_e64 v4, v65, v4, s[0:1]
	v_rsq_f32_e32 v63, v4
	v_lshl_add_u64 v[4:5], v[76:77], 0, s[18:19]
	v_mul_f32_e32 v65, 0x45800000, v63
	v_cndmask_b32_e64 v63, v63, v65, s[0:1]
	v_mul_f32_e32 v65, 0x4b800000, v64
	v_cndmask_b32_e32 v64, v64, v65, vcc
	v_rsq_f32_e32 v66, v64
	v_mov_b32_e32 v64, v60
	v_mov_b32_e32 v65, v58
	v_mov_b32_e32 v58, v61
	v_pk_add_f32 v[58:59], v[64:65], v[58:59]
	ds_bpermute_b32 v61, v137, v59
	ds_bpermute_b32 v60, v137, v58
	v_mul_f32_e32 v63, 0x3db504f3, v63
	v_mul_f32_e32 v64, 0x45800000, v66
	v_cndmask_b32_e32 v64, v66, v64, vcc
	v_mul_f32_e32 v66, v54, v63
	s_waitcnt lgkmcnt(0)
	v_pk_add_f32 v[58:59], v[58:59], v[60:61]
	ds_bpermute_b32 v61, v138, v59
	ds_bpermute_b32 v60, v138, v58
	v_mul_f32_e32 v63, v55, v63
	v_mov_b32_e32 v65, s44
	ds_read_b32 v65, v65
	s_waitcnt lgkmcnt(1)
	v_pk_add_f32 v[54:55], v[58:59], v[60:61]
	ds_bpermute_b32 v59, v139, v55
	ds_bpermute_b32 v58, v139, v54
	v_mul_f32_e32 v60, v52, v64
	v_cvt_pk_bf16_f32 v52, v66, s0
	v_mul_f32_e32 v61, v53, v64
	ds_write_b16 v143, v52
	s_waitcnt lgkmcnt(1)
	v_pk_add_f32 v[52:53], v[54:55], v[58:59]
	ds_bpermute_b32 v55, v140, v53
	ds_bpermute_b32 v54, v140, v52
	v_mul_f32_e32 v65, 0x3fb8aa3b, v65
	v_exp_f32_e32 v65, v65
	v_cvt_pk_bf16_f32 v58, v63, s0
	ds_write_b16 v144, v58
	s_waitcnt lgkmcnt(1)
	v_pk_add_f32 v[52:53], v[52:53], v[54:55]
	ds_bpermute_b32 v55, v141, v53
	ds_bpermute_b32 v54, v141, v52
	v_cvt_pk_bf16_f32 v58, v60, s0
	ds_write_b16 v145, v58
	v_cvt_pk_bf16_f32 v58, v61, s0
	ds_write_b16 v146, v58
	ds_write2st64_b32 v147, v60, v61 offset1:1
	s_waitcnt lgkmcnt(3)
	v_pk_add_f32 v[52:53], v[52:53], v[54:55]
	ds_bpermute_b32 v55, v142, v53
	ds_bpermute_b32 v54, v142, v52
	v_mul_f32_e32 v58, v65, v66
	v_cvt_pk_bf16_f32 v60, v58, s0
	v_lshl_add_u64 v[58:59], s[100:101], 1, v[4:5]
	global_store_short v[58:59], v60, off
	s_waitcnt lgkmcnt(0)
	v_pk_add_f32 v[52:53], v[52:53], v[54:55]
	v_mul_f32_e32 v60, v65, v63
	v_pk_add_f32 v[52:53], v[52:53], s[4:5] op_sel_hi:[1,0]
	s_nop 0
	v_mul_f32_e32 v54, 0x4b800000, v53
	v_cmp_gt_f32_e32 vcc, s65, v53
	s_nop 1
	v_cndmask_b32_e32 v53, v53, v54, vcc
	v_rsq_f32_e32 v53, v53
	v_cvt_pk_bf16_f32 v54, v60, s0
	global_store_short v[58:59], v54, off offset:128
	v_cmp_gt_f32_e64 s[0:1], s65, v52
	v_mul_f32_e32 v54, 0x45800000, v53
	v_cndmask_b32_e32 v53, v53, v54, vcc
	v_mul_f32_e32 v54, 0x3db504f3, v53
	v_mul_f32_e32 v53, 0x4b800000, v52
	v_cndmask_b32_e64 v52, v52, v53, s[0:1]
	v_rsq_f32_e32 v55, v52
	v_mov_b32_e32 v52, v56
	v_mov_b32_e32 v53, v50
	v_mov_b32_e32 v50, v57
	v_pk_add_f32 v[50:51], v[52:53], v[50:51]
	ds_bpermute_b32 v53, v137, v51
	ds_bpermute_b32 v52, v137, v50
	v_mov_b32_e32 v57, s45
	ds_read_b32 v57, v57
	v_mul_f32_e32 v56, 0x45800000, v55
	v_cndmask_b32_e64 v55, v55, v56, s[0:1]
	s_waitcnt lgkmcnt(1)
; __device__ __forceinline__ unsigned f2bf(float f) { return pk2(f, 0.f) & 0xffffu; }
; __device__ __forceinline__ float shfl_idx(float v, int src_lane) { return __builtin_bit_cast(float, __builtin_amdgcn_ds_bpermute(src_lane << 2, __builtin_bit_cast(int, v))); }
; __global__ void __launch_bounds__(512, 2) fwd_megakernel(Params kp_) {
;     ...
;                                     for (int o = 1; o < 64; o <<= 1) {
; #pragma unroll
;                                         for (int ii = 0; ii < 8; ++ii) { sq[ii] += shfl_idx(sq[ii], lane ^ o); sk[ii] += shfl_idx(sk[ii], lane ^ o); } }
; #pragma unroll
;                                     for (int ii = 0; ii < 8; ++ii) { const int i = wave * 8 + ii;
;                                         const float rq = rsqrtf(sq[ii] + EPS) * 0.08838834764831845f, rk = rsqrtf(sk[ii] + EPS);
;                                         const float eg = __expf(gc[i]);
;                                         const float qn0 = q0[ii] * rq, qn1 = q1[ii] * rq, kn0 = k0[ii] * rk, kn1 = k1[ii] * rk;
;                                         qbf[i * 136 + lane] = (bf16)f2bf(qn0); qbf[i * 136 + 64 + lane] = (bf16)f2bf(qn1);
;                                         kbf[i * 136 + lane] = (bf16)f2bf(kn0); kbf[i * 136 + 64 + lane] = (bf16)f2bf(kn1);
;                                         kc[i * 128 + lane] = kn0; kc[i * 128 + 64 + lane] = kn1;
;                                         bf16* qd = QDbuf + (size_t)item * 8192 + i * 128; qd[lane] = (bf16)f2bf(qn0 * eg); qd[64 + lane] = (bf16)f2bf(qn1 * eg);
	v_pk_add_f32 v[50:51], v[50:51], v[52:53]
	ds_bpermute_b32 v53, v138, v51
	ds_bpermute_b32 v52, v138, v50
	s_waitcnt lgkmcnt(2)
	v_mul_f32_e32 v56, 0x3fb8aa3b, v57
	v_mul_f32_e32 v57, v48, v54
	v_mul_f32_e32 v54, v49, v54
	v_exp_f32_e32 v56, v56
	s_waitcnt lgkmcnt(0)
	v_pk_add_f32 v[48:49], v[50:51], v[52:53]
	ds_bpermute_b32 v51, v139, v49
	ds_bpermute_b32 v50, v139, v48
	v_mul_f32_e32 v52, v46, v55
	v_cvt_pk_bf16_f32 v46, v57, s0
	v_mul_f32_e32 v53, v47, v55
	ds_write_b16 v148, v46
	s_waitcnt lgkmcnt(1)
	v_pk_add_f32 v[46:47], v[48:49], v[50:51]
	ds_bpermute_b32 v49, v140, v47
	ds_bpermute_b32 v48, v140, v46
	v_cvt_pk_bf16_f32 v50, v54, s0
	ds_write_b16 v149, v50
	v_cvt_pk_bf16_f32 v50, v52, s0
	ds_write_b16 v150, v50
	s_waitcnt lgkmcnt(2)
	v_pk_add_f32 v[46:47], v[46:47], v[48:49]
	ds_bpermute_b32 v49, v141, v47
	ds_bpermute_b32 v48, v141, v46
	v_cvt_pk_bf16_f32 v50, v53, s0
	ds_write_b16 v151, v50
	ds_write2st64_b32 v152, v52, v53 offset1:1
	v_mul_f32_e32 v50, v56, v57
	v_cvt_pk_bf16_f32 v52, v50, s0
	s_waitcnt lgkmcnt(2)
	v_pk_add_f32 v[46:47], v[46:47], v[48:49]
	ds_bpermute_b32 v49, v142, v47
	ds_bpermute_b32 v48, v142, v46
	v_readlane_b32 s0, v255, 42
	v_readlane_b32 s1, v255, 43
	s_waitcnt lgkmcnt(0)
	v_pk_add_f32 v[46:47], v[46:47], v[48:49]
	s_nop 0
	v_pk_add_f32 v[46:47], v[46:47], s[4:5] op_sel_hi:[1,0]
	v_lshl_add_u64 v[50:51], s[0:1], 1, v[4:5]
	v_mul_f32_e32 v48, 0x4b800000, v47
	v_cmp_gt_f32_e32 vcc, s65, v47
	global_store_short v[50:51], v52, off
	v_mul_f32_e32 v52, v56, v54
	v_cndmask_b32_e32 v47, v47, v48, vcc
	v_rsq_f32_e32 v47, v47
	v_cvt_pk_bf16_f32 v48, v52, s0
	global_store_short v[50:51], v48, off offset:128
	v_cmp_gt_f32_e64 s[0:1], s65, v46
	v_mul_f32_e32 v48, 0x45800000, v47
	v_cndmask_b32_e32 v47, v47, v48, vcc
	v_mul_f32_e32 v48, 0x3db504f3, v47
	v_mul_f32_e32 v47, 0x4b800000, v46
	v_cndmask_b32_e64 v46, v46, v47, s[0:1]
	v_rsq_f32_e32 v49, v46
	v_mov_b32_e32 v46, v44
	v_mov_b32_e32 v47, v42
	v_mov_b32_e32 v42, v45
	v_pk_add_f32 v[42:43], v[46:47], v[42:43]
	ds_bpermute_b32 v45, v137, v43
	ds_bpermute_b32 v44, v137, v42
	v_mul_f32_e32 v46, 0x45800000, v49
	v_cndmask_b32_e64 v46, v49, v46, s[0:1]
	v_mul_f32_e32 v49, v34, v48
	v_mul_f32_e32 v48, v35, v48
	s_waitcnt lgkmcnt(0)
	v_pk_add_f32 v[42:43], v[42:43], v[44:45]
	ds_bpermute_b32 v45, v138, v43
	ds_bpermute_b32 v44, v138, v42
	v_readlane_b32 s5, v255, 44
	s_waitcnt lgkmcnt(0)
	v_pk_add_f32 v[34:35], v[42:43], v[44:45]
	ds_bpermute_b32 v43, v139, v35
	ds_bpermute_b32 v42, v139, v34
	v_mul_f32_e32 v44, v36, v46
	v_cvt_pk_bf16_f32 v36, v49, s0
	v_mul_f32_e32 v45, v37, v46
	ds_write_b16 v153, v36
	s_waitcnt lgkmcnt(1)
	v_pk_add_f32 v[34:35], v[34:35], v[42:43]
	ds_bpermute_b32 v37, v140, v35
	ds_bpermute_b32 v36, v140, v34
	v_mov_b32_e32 v47, s5
	ds_read_b32 v47, v47
	v_cvt_pk_bf16_f32 v42, v48, s0
	ds_write_b16 v154, v42
	s_waitcnt lgkmcnt(2)
	v_pk_add_f32 v[34:35], v[34:35], v[36:37]
	ds_bpermute_b32 v37, v141, v35
	ds_bpermute_b32 v36, v141, v34
	s_waitcnt lgkmcnt(3)
	v_mul_f32_e32 v47, 0x3fb8aa3b, v47
	v_exp_f32_e32 v47, v47
	v_cvt_pk_bf16_f32 v42, v44, s0
	ds_write_b16 v155, v42
	s_waitcnt lgkmcnt(1)
	v_pk_add_f32 v[34:35], v[34:35], v[36:37]
	ds_bpermute_b32 v37, v142, v35
	ds_bpermute_b32 v36, v142, v34
	v_cvt_pk_bf16_f32 v42, v45, s0
	ds_write_b16 v156, v42
	ds_write2st64_b32 v157, v44, v45 offset1:1
	v_mul_f32_e32 v42, v47, v49
	v_cvt_pk_bf16_f32 v44, v42, s0
	s_waitcnt lgkmcnt(2)
	v_pk_add_f32 v[34:35], v[34:35], v[36:37]
	v_readlane_b32 s0, v255, 45
	v_pk_add_f32 v[34:35], v[34:35], s[4:5] op_sel_hi:[1,0]
	v_readlane_b32 s1, v255, 46
	v_mul_f32_e32 v36, 0x4b800000, v35
	v_cmp_gt_f32_e32 vcc, s65, v35
	v_lshl_add_u64 v[42:43], s[0:1], 1, v[4:5]
	global_store_short v[42:43], v44, off
	v_cndmask_b32_e32 v35, v35, v36, vcc
	v_rsq_f32_e32 v35, v35
	v_mul_f32_e32 v44, v47, v48
	v_cvt_pk_bf16_f32 v36, v44, s0
	global_store_short v[42:43], v36, off offset:128
	v_mul_f32_e32 v36, 0x45800000, v35
	v_cndmask_b32_e32 v35, v35, v36, vcc
	v_cmp_gt_f32_e64 s[0:1], s65, v34
	v_mul_f32_e32 v42, 0x3db504f3, v35
	v_mul_f32_e32 v35, 0x4b800000, v34
	v_cndmask_b32_e64 v34, v34, v35, s[0:1]
	v_rsq_f32_e32 v43, v34
	v_mov_b32_e32 v34, v40
	v_mov_b32_e32 v35, v38
	v_mov_b32_e32 v38, v41
	v_pk_add_f32 v[34:35], v[34:35], v[38:39]
	ds_bpermute_b32 v37, v137, v35
	ds_bpermute_b32 v36, v137, v34
	v_mul_f32_e32 v40, v26, v42
	v_mul_f32_e32 v41, v27, v42
	v_mul_f32_e32 v38, 0x45800000, v43
	v_cndmask_b32_e64 v38, v43, v38, s[0:1]
	s_waitcnt lgkmcnt(0)
	v_pk_add_f32 v[34:35], v[34:35], v[36:37]
	ds_bpermute_b32 v37, v138, v35
	ds_bpermute_b32 v36, v138, v34
	v_readlane_b32 s5, v255, 47
	s_waitcnt lgkmcnt(0)
	v_pk_add_f32 v[26:27], v[34:35], v[36:37]
	ds_bpermute_b32 v35, v139, v27
	ds_bpermute_b32 v34, v139, v26
	v_mul_f32_e32 v36, v28, v38
	v_cvt_pk_bf16_f32 v28, v40, s0
	v_mul_f32_e32 v37, v29, v38
	ds_write_b16 v158, v28
	s_waitcnt lgkmcnt(1)
	v_pk_add_f32 v[26:27], v[26:27], v[34:35]
	ds_bpermute_b32 v29, v140, v27
	ds_bpermute_b32 v28, v140, v26
	v_mov_b32_e32 v39, s5
	ds_read_b32 v39, v39
	v_cvt_pk_bf16_f32 v34, v41, s0
	ds_write_b16 v159, v34
	s_waitcnt lgkmcnt(2)
	v_pk_add_f32 v[26:27], v[26:27], v[28:29]
	ds_bpermute_b32 v29, v141, v27
	ds_bpermute_b32 v28, v141, v26
	s_waitcnt lgkmcnt(3)
	v_mul_f32_e32 v39, 0x3fb8aa3b, v39
	v_exp_f32_e32 v39, v39
	v_cvt_pk_bf16_f32 v34, v36, s0
	ds_write_b16 v160, v34
	s_waitcnt lgkmcnt(1)
	v_pk_add_f32 v[26:27], v[26:27], v[28:29]
	ds_bpermute_b32 v29, v142, v27
	ds_bpermute_b32 v28, v142, v26
	v_cvt_pk_bf16_f32 v34, v37, s0
	ds_write_b16 v161, v34
	ds_write2st64_b32 v162, v36, v37 offset1:1
	v_mul_f32_e32 v34, v39, v40
	v_cvt_pk_bf16_f32 v36, v34, s0
	s_waitcnt lgkmcnt(2)
; __device__ __forceinline__ unsigned f2bf(float f) { return pk2(f, 0.f) & 0xffffu; }
; __device__ __forceinline__ float shfl_idx(float v, int src_lane) { return __builtin_bit_cast(float, __builtin_amdgcn_ds_bpermute(src_lane << 2, __builtin_bit_cast(int, v))); }
; __global__ void __launch_bounds__(512, 2) fwd_megakernel(Params kp_) {
;     ...
;                                     for (int o = 1; o < 64; o <<= 1) {
; #pragma unroll
;                                         for (int ii = 0; ii < 8; ++ii) { sq[ii] += shfl_idx(sq[ii], lane ^ o); sk[ii] += shfl_idx(sk[ii], lane ^ o); } }
; #pragma unroll
;                                     for (int ii = 0; ii < 8; ++ii) { const int i = wave * 8 + ii;
;                                         const float rq = rsqrtf(sq[ii] + EPS) * 0.08838834764831845f, rk = rsqrtf(sk[ii] + EPS);
;                                         const float eg = __expf(gc[i]);
;                                         const float qn0 = q0[ii] * rq, qn1 = q1[ii] * rq, kn0 = k0[ii] * rk, kn1 = k1[ii] * rk;
;                                         qbf[i * 136 + lane] = (bf16)f2bf(qn0); qbf[i * 136 + 64 + lane] = (bf16)f2bf(qn1);
;                                         kbf[i * 136 + lane] = (bf16)f2bf(kn0); kbf[i * 136 + 64 + lane] = (bf16)f2bf(kn1);
;                                         kc[i * 128 + lane] = kn0; kc[i * 128 + 64 + lane] = kn1;
;                                         bf16* qd = QDbuf + (size_t)item * 8192 + i * 128; qd[lane] = (bf16)f2bf(qn0 * eg); qd[64 + lane] = (bf16)f2bf(qn1 * eg);
	v_pk_add_f32 v[26:27], v[26:27], v[28:29]
	v_readlane_b32 s0, v255, 48
	v_pk_add_f32 v[26:27], v[26:27], s[4:5] op_sel_hi:[1,0]
	v_readlane_b32 s1, v255, 49
	v_mul_f32_e32 v28, 0x4b800000, v27
	v_cmp_gt_f32_e32 vcc, s65, v27
	v_lshl_add_u64 v[34:35], s[0:1], 1, v[4:5]
	global_store_short v[34:35], v36, off
	v_cndmask_b32_e32 v27, v27, v28, vcc
	v_rsq_f32_e32 v27, v27
	v_mul_f32_e32 v36, v39, v41
	v_cvt_pk_bf16_f32 v28, v36, s0
	global_store_short v[34:35], v28, off offset:128
	v_mul_f32_e32 v28, 0x45800000, v27
	v_cndmask_b32_e32 v27, v27, v28, vcc
	v_cmp_gt_f32_e64 s[0:1], s65, v26
	v_mul_f32_e32 v34, 0x3db504f3, v27
	v_mul_f32_e32 v27, 0x4b800000, v26
	v_cndmask_b32_e64 v26, v26, v27, s[0:1]
	v_rsq_f32_e32 v35, v26
	v_mov_b32_e32 v26, v32
	v_mov_b32_e32 v27, v30
	v_mov_b32_e32 v30, v33
	v_pk_add_f32 v[26:27], v[26:27], v[30:31]
	ds_bpermute_b32 v29, v137, v27
	ds_bpermute_b32 v28, v137, v26
	v_mul_f32_e32 v32, v22, v34
	v_mul_f32_e32 v33, v23, v34
	v_mul_f32_e32 v30, 0x45800000, v35
	v_cndmask_b32_e64 v30, v35, v30, s[0:1]
	s_waitcnt lgkmcnt(0)
	v_pk_add_f32 v[26:27], v[26:27], v[28:29]
	ds_bpermute_b32 v29, v138, v27
	ds_bpermute_b32 v28, v138, v26
	v_readlane_b32 s5, v255, 50
	s_waitcnt lgkmcnt(0)
	v_pk_add_f32 v[22:23], v[26:27], v[28:29]
	ds_bpermute_b32 v27, v139, v23
	ds_bpermute_b32 v26, v139, v22
	v_mul_f32_e32 v28, v24, v30
	v_cvt_pk_bf16_f32 v24, v32, s0
	v_mul_f32_e32 v29, v25, v30
	ds_write_b16 v163, v24
	s_waitcnt lgkmcnt(1)
	v_pk_add_f32 v[22:23], v[22:23], v[26:27]
	ds_bpermute_b32 v25, v140, v23
	ds_bpermute_b32 v24, v140, v22
	v_mov_b32_e32 v31, s5
	ds_read_b32 v31, v31
	v_cvt_pk_bf16_f32 v26, v33, s0
	ds_write_b16 v164, v26
	s_waitcnt lgkmcnt(2)
	v_pk_add_f32 v[22:23], v[22:23], v[24:25]
	ds_bpermute_b32 v25, v141, v23
	ds_bpermute_b32 v24, v141, v22
	s_waitcnt lgkmcnt(3)
	v_mul_f32_e32 v31, 0x3fb8aa3b, v31
	v_exp_f32_e32 v31, v31
	v_cvt_pk_bf16_f32 v26, v28, s0
	ds_write_b16 v165, v26
	s_waitcnt lgkmcnt(1)
	v_pk_add_f32 v[22:23], v[22:23], v[24:25]
	ds_bpermute_b32 v25, v142, v23
	ds_bpermute_b32 v24, v142, v22
	v_cvt_pk_bf16_f32 v26, v29, s0
	ds_write_b16 v166, v26
	ds_write2st64_b32 v167, v28, v29 offset1:1
	v_mul_f32_e32 v26, v31, v32
	v_cvt_pk_bf16_f32 v28, v26, s0
	s_waitcnt lgkmcnt(2)
	v_pk_add_f32 v[22:23], v[22:23], v[24:25]
	v_readlane_b32 s0, v255, 51
	v_pk_add_f32 v[22:23], v[22:23], s[4:5] op_sel_hi:[1,0]
	v_readlane_b32 s1, v255, 52
	v_mul_f32_e32 v24, 0x4b800000, v23
	v_cmp_gt_f32_e32 vcc, s65, v23
	v_lshl_add_u64 v[26:27], s[0:1], 1, v[4:5]
	global_store_short v[26:27], v28, off
	v_cndmask_b32_e32 v23, v23, v24, vcc
	v_rsq_f32_e32 v23, v23
	v_mul_f32_e32 v28, v31, v33
	v_cvt_pk_bf16_f32 v24, v28, s0
	global_store_short v[26:27], v24, off offset:128
	v_mul_f32_e32 v24, 0x45800000, v23
	v_cndmask_b32_e32 v23, v23, v24, vcc
	v_cmp_gt_f32_e64 s[0:1], s65, v22
	v_mul_f32_e32 v24, 0x3db504f3, v23
	v_mul_f32_e32 v23, 0x4b800000, v22
	v_cndmask_b32_e64 v22, v22, v23, s[0:1]
	v_rsq_f32_e32 v25, v22
	v_mov_b32_e32 v22, v20
	v_mov_b32_e32 v23, v18
	v_mov_b32_e32 v18, v21
	v_pk_add_f32 v[18:19], v[22:23], v[18:19]
	ds_bpermute_b32 v21, v137, v19
	ds_bpermute_b32 v20, v137, v18
	v_mul_f32_e32 v22, 0x45800000, v25
	v_cndmask_b32_e64 v22, v25, v22, s[0:1]
	v_mul_f32_e32 v25, v14, v24
	v_mul_f32_e32 v24, v15, v24
	s_waitcnt lgkmcnt(0)
	v_pk_add_f32 v[18:19], v[18:19], v[20:21]
	ds_bpermute_b32 v21, v138, v19
	ds_bpermute_b32 v20, v138, v18
	v_readlane_b32 s5, v255, 53
	s_waitcnt lgkmcnt(0)
	v_pk_add_f32 v[14:15], v[18:19], v[20:21]
	ds_bpermute_b32 v19, v139, v15
	ds_bpermute_b32 v18, v139, v14
	v_mul_f32_e32 v20, v16, v22
	v_cvt_pk_bf16_f32 v16, v25, s0
	v_mul_f32_e32 v21, v17, v22
	ds_write_b16 v168, v16
	s_waitcnt lgkmcnt(1)
	v_pk_add_f32 v[14:15], v[14:15], v[18:19]
	ds_bpermute_b32 v17, v140, v15
	ds_bpermute_b32 v16, v140, v14
	v_mov_b32_e32 v23, s5
	ds_read_b32 v23, v23
	v_cvt_pk_bf16_f32 v18, v24, s0
	ds_write_b16 v169, v18
	s_waitcnt lgkmcnt(2)
	v_pk_add_f32 v[14:15], v[14:15], v[16:17]
	ds_bpermute_b32 v17, v141, v15
	ds_bpermute_b32 v16, v141, v14
	s_waitcnt lgkmcnt(3)
	v_mul_f32_e32 v23, 0x3fb8aa3b, v23
	v_exp_f32_e32 v23, v23
	v_cvt_pk_bf16_f32 v18, v20, s0
	ds_write_b16 v170, v18
	s_waitcnt lgkmcnt(1)
; __device__ __forceinline__ unsigned f2bf(float f) { return pk2(f, 0.f) & 0xffffu; }
; __device__ __forceinline__ float shfl_idx(float v, int src_lane) { return __builtin_bit_cast(float, __builtin_amdgcn_ds_bpermute(src_lane << 2, __builtin_bit_cast(int, v))); }
; __global__ void __launch_bounds__(512, 2) fwd_megakernel(Params kp_) {
;     ...
;                                     for (int o = 1; o < 64; o <<= 1) {
; #pragma unroll
;                                         for (int ii = 0; ii < 8; ++ii) { sq[ii] += shfl_idx(sq[ii], lane ^ o); sk[ii] += shfl_idx(sk[ii], lane ^ o); } }
; #pragma unroll
;                                     for (int ii = 0; ii < 8; ++ii) { const int i = wave * 8 + ii;
;                                         const float rq = rsqrtf(sq[ii] + EPS) * 0.08838834764831845f, rk = rsqrtf(sk[ii] + EPS);
;                                         const float eg = __expf(gc[i]);
;                                         const float qn0 = q0[ii] * rq, qn1 = q1[ii] * rq, kn0 = k0[ii] * rk, kn1 = k1[ii] * rk;
;                                         qbf[i * 136 + lane] = (bf16)f2bf(qn0); qbf[i * 136 + 64 + lane] = (bf16)f2bf(qn1);
;                                         kbf[i * 136 + lane] = (bf16)f2bf(kn0); kbf[i * 136 + 64 + lane] = (bf16)f2bf(kn1);
;                                         kc[i * 128 + lane] = kn0; kc[i * 128 + 64 + lane] = kn1;
;                                         bf16* qd = QDbuf + (size_t)item * 8192 + i * 128; qd[lane] = (bf16)f2bf(qn0 * eg); qd[64 + lane] = (bf16)f2bf(qn1 * eg);
;                                     }
;                                 }
;                                 if (tid == 0) gle[item] = __expf(gl);
	v_pk_add_f32 v[14:15], v[14:15], v[16:17]
	ds_bpermute_b32 v17, v142, v15
	ds_bpermute_b32 v16, v142, v14
	v_cvt_pk_bf16_f32 v18, v21, s0
	ds_write_b16 v171, v18
	ds_write2st64_b32 v172, v20, v21 offset1:1
	v_mul_f32_e32 v18, v23, v25
	v_cvt_pk_bf16_f32 v20, v18, s0
	s_waitcnt lgkmcnt(2)
	v_pk_add_f32 v[14:15], v[14:15], v[16:17]
	v_readlane_b32 s0, v255, 54
	v_pk_add_f32 v[14:15], v[14:15], s[4:5] op_sel_hi:[1,0]
	v_readlane_b32 s1, v255, 55
	v_mul_f32_e32 v16, 0x4b800000, v15
	v_cmp_gt_f32_e32 vcc, s65, v15
	v_lshl_add_u64 v[18:19], s[0:1], 1, v[4:5]
	global_store_short v[18:19], v20, off
	v_cndmask_b32_e32 v15, v15, v16, vcc
	v_rsq_f32_e32 v15, v15
	v_mul_f32_e32 v20, v23, v24
	v_cvt_pk_bf16_f32 v16, v20, s0
	global_store_short v[18:19], v16, off offset:128
	v_mul_f32_e32 v16, 0x45800000, v15
	v_cndmask_b32_e32 v15, v15, v16, vcc
	v_cmp_gt_f32_e64 s[0:1], s65, v14
	v_mul_f32_e32 v16, 0x3db504f3, v15
	v_mul_f32_e32 v15, 0x4b800000, v14
	v_cndmask_b32_e64 v14, v14, v15, s[0:1]
	v_rsq_f32_e32 v17, v14
	v_mov_b32_e32 v14, v12
	v_mov_b32_e32 v15, v10
	v_mov_b32_e32 v10, v13
	v_pk_add_f32 v[10:11], v[14:15], v[10:11]
	ds_bpermute_b32 v13, v137, v11
	ds_bpermute_b32 v12, v137, v10
	v_mul_f32_e32 v14, 0x45800000, v17
	v_cndmask_b32_e64 v14, v17, v14, s[0:1]
	v_mul_f32_e32 v17, v8, v16
	v_mul_f32_e32 v16, v9, v16
	s_waitcnt lgkmcnt(0)
	v_pk_add_f32 v[10:11], v[10:11], v[12:13]
	ds_bpermute_b32 v13, v138, v11
	ds_bpermute_b32 v12, v138, v10
	v_readlane_b32 s5, v255, 56
	s_waitcnt lgkmcnt(0)
	v_pk_add_f32 v[8:9], v[10:11], v[12:13]
	ds_bpermute_b32 v11, v139, v9
	ds_bpermute_b32 v10, v139, v8
	v_mul_f32_e32 v12, v6, v14
	v_cvt_pk_bf16_f32 v6, v17, s0
	v_mul_f32_e32 v13, v7, v14
	ds_write_b16 v173, v6
	s_waitcnt lgkmcnt(1)
	v_pk_add_f32 v[6:7], v[8:9], v[10:11]
	ds_bpermute_b32 v9, v140, v7
	ds_bpermute_b32 v8, v140, v6
	v_mov_b32_e32 v15, s5
	ds_read_b32 v15, v15
	v_cvt_pk_bf16_f32 v10, v16, s0
	ds_write_b16 v174, v10
	s_waitcnt lgkmcnt(2)
	v_pk_add_f32 v[6:7], v[6:7], v[8:9]
	ds_bpermute_b32 v9, v141, v7
	ds_bpermute_b32 v8, v141, v6
	s_waitcnt lgkmcnt(3)
	v_mul_f32_e32 v15, 0x3fb8aa3b, v15
	v_exp_f32_e32 v15, v15
	v_cvt_pk_bf16_f32 v10, v12, s0
	ds_write_b16 v175, v10
	s_waitcnt lgkmcnt(1)
	v_pk_add_f32 v[6:7], v[6:7], v[8:9]
	ds_bpermute_b32 v9, v142, v7
	ds_bpermute_b32 v8, v142, v6
	v_cvt_pk_bf16_f32 v10, v13, s0
	ds_write_b16 v176, v10
	ds_write2st64_b32 v177, v12, v13 offset1:1
	v_mul_f32_e32 v10, v15, v17
	v_cvt_pk_bf16_f32 v12, v10, s0
	s_waitcnt lgkmcnt(2)
	v_pk_add_f32 v[6:7], v[6:7], v[8:9]
	v_lshl_add_u64 v[10:11], s[14:15], 1, v[4:5]
	v_pk_add_f32 v[6:7], v[6:7], s[4:5] op_sel_hi:[1,0]
	global_store_short v[10:11], v12, off
	v_mul_f32_e32 v12, v15, v16
	v_mul_f32_e32 v8, 0x4b800000, v7
	v_cmp_gt_f32_e32 vcc, s65, v7
	v_mul_f32_e32 v9, 0x4b800000, v6
	v_readlane_b32 s4, v255, 57
	v_cndmask_b32_e32 v7, v7, v8, vcc
	v_cvt_pk_bf16_f32 v8, v12, s0
	v_cmp_gt_f32_e64 s[0:1], s65, v6
	v_rsq_f32_e32 v7, v7
	global_store_short v[10:11], v8, off offset:128
	v_cndmask_b32_e64 v6, v6, v9, s[0:1]
	v_mov_b32_e32 v9, s4
	v_rsq_f32_e32 v6, v6
	ds_read_b32 v9, v9
	v_mul_f32_e32 v8, 0x45800000, v7
	v_cndmask_b32_e32 v7, v7, v8, vcc
	v_mul_f32_e32 v8, 0x45800000, v6
	v_mul_f32_e32 v7, 0x3db504f3, v7
	v_cndmask_b32_e64 v6, v6, v8, s[0:1]
	s_waitcnt lgkmcnt(0)
	v_mul_f32_e32 v8, 0x3fb8aa3b, v9
	v_exp_f32_e32 v8, v8
	v_mul_f32_e32 v0, v0, v7
	v_mul_f32_e32 v7, v1, v7
	v_mul_f32_e32 v1, v2, v6
	v_mul_f32_e32 v2, v3, v6
	v_cvt_pk_bf16_f32 v3, v0, s0
	ds_write_b16 v178, v3
	v_cvt_pk_bf16_f32 v3, v7, s0
	ds_write_b16 v179, v3
	v_cvt_pk_bf16_f32 v3, v1, s0
	ds_write_b16 v180, v3
	v_cvt_pk_bf16_f32 v3, v2, s0
	v_mul_f32_e32 v0, v8, v0
	ds_write_b16 v181, v3
	ds_write2st64_b32 v182, v1, v2 offset1:1
	v_cvt_pk_bf16_f32 v2, v0, s0
	v_lshl_add_u64 v[0:1], s[16:17], 1, v[4:5]
	global_store_short v[0:1], v2, off
	v_mul_f32_e32 v2, v8, v7
	v_cvt_pk_bf16_f32 v2, v2, s0
	global_store_short v[0:1], v2, off offset:128
	s_and_saveexec_b64 s[0:1], s[40:41]
	s_cbranch_execz .LBB0_700
	v_mul_f32_e32 v0, 0x3fb8aa3b, v62
	v_exp_f32_e32 v0, v0
	s_lshl_b64 s[4:5], s[2:3], 2
	v_readlane_b32 s3, v253, 10
	s_add_u32 s4, s3, s4
	v_readlane_b32 s3, v253, 11
	s_addc_u32 s5, s3, s5
	global_store_dword v197, v0, s[4:5]

; __global__ void __launch_bounds__(512, 2) fwd_megakernel(Params kp_) {
;     ...
;                                 for (int ib = 0; ib < 4; ++ib) {
;                                     float r[16];
; #pragma unroll
;                                     for (int i = 0; i < 16; ++i) { const int row = ib * 16 + i; float v0 = X[row * 128] * bet[row]; if (!isu) v0 *= __expf(gc[row]); r[i] = v0; }
; #pragma unroll 1
;                                     for (int jb = 0; jb < ib; ++jb) {
;                                         float xj[16];
; #pragma unroll
;                                         for (int jj = 0; jj < 16; ++jj) xj[jj] = X[(jb * 16 + jj) * 128];
; #pragma unroll
;                                         for (int i = 0; i < 16; ++i) { const f32x4* lr = Ls4 + (ib * 16 + i) * 16 + jb * 4;
;                                             const f32x4 l0 = lr[0], l1 = lr[1], l2 = lr[2], l3 = lr[3];
;                                             r[i] -= ((l0.x * xj[0] + l0.y * xj[1]) + (l0.z * xj[2] + l0.w * xj[3])) + ((l1.x * xj[4] + l1.y * xj[5]) + (l1.z * xj[6] + l1.w * xj[7]))
;                                                   + ((l2.x * xj[8] + l2.y * xj[9]) + (l2.z * xj[10] + l2.w * xj[11])) + ((l3.x * xj[12] + l3.y * xj[13]) + (l3.z * xj[14] + l3.w * xj[15])); }
;                                     }
; #pragma unroll
;                                     for (int i = 1; i < 16; ++i) { const float* lr = Ls + (ib * 16 + i) * 64 + ib * 16;
; #pragma unroll
;                                         for (int j = 0; j < i; ++j) r[i] -= lr[j] * r[j]; }
.LBB0_754:
	s_lshl_b32 s18, s27, 2
	s_add_i32 s18, s18, 0
	s_add_i32 s18, s18, 0x10000
	s_lshl_b32 s8, s8, 8
	s_add_i32 s8, s18, s8
	s_lshl_b32 s19, s94, 8
	v_mov_b32_e32 v1, s8
	s_lshl_b32 s8, s25, 8
	s_add_i32 s19, s18, s19
	s_add_i32 s8, s18, s8
	v_mov_b32_e32 v0, s19
	v_mov_b32_e32 v3, s8
	ds_read_b96 v[4:6], v3
	ds_read_b32 v51, v0
	ds_read_b96 v[0:2], v1
	s_lshl_b32 s8, s9, 8
	s_lshl_b32 s9, s23, 8
	s_add_i32 s9, s18, s9
	ds_read2_b32 v[68:69], v3 offset0:3 offset1:4
	v_mov_b32_e32 v3, s9
	s_waitcnt lgkmcnt(3)
	v_mov_b32_e32 v71, v6
	ds_read_b96 v[6:8], v3
	ds_read2_b32 v[72:73], v3 offset0:3 offset1:4
	s_lshl_b32 s19, vcc_lo, 8
	s_add_i32 s19, s18, s19
	v_mov_b32_e32 v66, s19
	s_waitcnt lgkmcnt(1)
	v_mov_b32_e32 v75, v8
	ds_read_b96 v[8:10], v66
	ds_read2_b32 v[86:87], v3 offset0:5 offset1:6
	s_lshl_b32 s7, s7, 8
	s_lshl_b32 s9, s22, 8
	s_add_i32 s7, s18, s7
	s_lshl_b32 s22, s33, 8
	v_mov_b32_e32 v3, s7
	s_add_i32 s22, s18, s22
	s_waitcnt lgkmcnt(1)
	v_mov_b32_e32 v89, v10
	ds_read_b96 v[10:12], v3
	ds_read2_b32 v[90:91], v3 offset0:3 offset1:4
	v_mov_b32_e32 v13, s22
	s_lshl_b32 s22, s24, 8
	s_add_i32 s22, s18, s22
	v_mov_b32_e32 v70, v5
	v_fma_f32 v65, -v34, v4, v39
	v_mov_b32_e32 v74, v7
	v_fma_f32 v215, -v34, v6, v41
	v_mov_b32_e32 v226, s22
	ds_read_b128 v[4:7], v13 offset:32
	ds_read_b96 v[16:18], v226
	s_lshl_b32 s4, s4, 8
	v_mov_b32_e32 v88, v9
	v_fma_f32 v230, -v34, v8, v43
	s_waitcnt lgkmcnt(3)
	v_mov_b32_e32 v92, v11
	v_mov_b32_e32 v93, v12
	v_fma_f32 v231, -v34, v10, v45
	ds_read_b128 v[8:11], v13
	ds_read_b128 v[12:15], v13 offset:16
	s_add_i32 s4, s18, s4
	v_mov_b32_e32 v24, s4
	s_waitcnt lgkmcnt(2)
	v_mov_b32_e32 v94, v17
	v_mov_b32_e32 v95, v18
	v_fma_f32 v232, -v34, v16, v47
	ds_read_b128 v[16:19], v24
	s_add_i32 s8, s18, s8
	s_lshl_b32 s4, s5, 8
	s_add_i32 s4, s18, s4
	s_waitcnt lgkmcnt(2)
	v_mov_b32_e32 v50, v8
	v_mov_b32_e32 v8, s8
	s_add_i32 s9, s18, s9
	v_mov_b32_e32 v233, s4
	ds_read_b64 v[96:97], v24 offset:48
	ds_read_b96 v[62:64], v233
	ds_read_b128 v[20:23], v24 offset:16
	ds_read_b128 v[24:27], v24 offset:32
	ds_read2_b32 v[200:201], v226 offset0:11 offset1:12
	ds_read_b128 v[28:31], v8
	v_mov_b32_e32 v47, v35
	v_mov_b32_e32 v8, s9
	s_waitcnt lgkmcnt(6)
	v_fma_f32 v16, -v34, v16, v48
	s_waitcnt lgkmcnt(4)
	v_fma_f32 v45, -v34, v62, v49
	v_pk_fma_f32 v[202:203], v[34:35], v[50:51], v[46:47] op_sel_hi:[0,1,1] neg_lo:[1,0,0] neg_hi:[1,0,0]
	ds_read_b128 v[46:49], v8
	v_mov_b32_e32 v35, v203
	s_waitcnt lgkmcnt(1)
	v_pk_mul_f32 v[28:29], v[34:35], v[28:29]
	s_lshl_b32 s19, s26, 8
	v_sub_f32_e32 v28, v38, v28
	s_add_i32 s19, s18, s19
	s_lshl_b32 s7, vcc_hi, 8
	v_sub_f32_e32 v234, v28, v29
	s_waitcnt lgkmcnt(0)
	v_pk_mul_f32 v[28:29], v[34:35], v[46:47]
	s_add_i32 s7, s18, s7
	v_mov_b32_e32 v38, s19
	ds_read_b64 v[216:217], v8 offset:16
	ds_read_b128 v[50:53], v38
	v_sub_f32_e32 v8, v40, v28
	v_sub_f32_e32 v235, v8, v29
	v_mov_b32_e32 v8, s7
	ds_read_b128 v[38:41], v38 offset:16
	ds_read_b128 v[54:57], v8
	s_waitcnt lgkmcnt(2)
	v_pk_mul_f32 v[28:29], v[34:35], v[50:51]
	s_lshl_b32 s6, s6, 8
	v_sub_f32_e32 v28, v42, v28
	s_add_i32 s6, s18, s6
	s_waitcnt lgkmcnt(0)
	v_pk_mul_f32 v[42:43], v[34:35], v[54:55]
	v_sub_f32_e32 v236, v28, v29
	ds_read_b128 v[58:61], v8 offset:16
	ds_read_b64 v[28:29], v8 offset:32
	v_sub_f32_e32 v8, v44, v42
	v_sub_f32_e32 v35, v8, v43
	v_fma_f32 v237, -v203, v9, v202
	v_fma_f32 v238, -v203, v17, v16
	v_fma_f32 v241, -v203, v63, v45
	ds_read2_b32 v[8:9], v233 offset0:3 offset1:4
	ds_read2_b32 v[16:17], v233 offset0:5 offset1:6
	ds_read2_b32 v[42:43], v233 offset0:7 offset1:8
	ds_read2_b32 v[44:45], v233 offset0:9 offset1:10
	ds_read2_b32 v[46:47], v233 offset0:11 offset1:12
	ds_read2_b32 v[50:51], v3 offset0:9 offset1:10
	ds_read2_b32 v[54:55], v3 offset0:7 offset1:8
	ds_read2_b32 v[62:63], v3 offset0:5 offset1:6
	v_mov_b32_e32 v3, s6
	ds_read_b64 v[218:219], v3
	ds_read2_b32 v[220:221], v226 offset0:9 offset1:10
	ds_read2_b32 v[222:223], v226 offset0:7 offset1:8
	ds_read2_b32 v[224:225], v226 offset0:5 offset1:6
	ds_read2_b32 v[226:227], v226 offset0:3 offset1:4
	s_waitcnt lgkmcnt(4)
	v_mov_b32_e32 v228, v218
	v_mov_b32_e32 v229, v0
	v_pk_fma_f32 v[36:37], v[34:35], v[228:229], v[36:37] op_sel_hi:[0,1,1] neg_lo:[1,0,0] neg_hi:[1,0,0]
	v_mov_b32_e32 v0, v219
	v_pk_fma_f32 v[0:1], v[202:203], v[0:1], v[36:37] op_sel:[1,0,0] neg_lo:[1,0,0] neg_hi:[1,0,0]
	s_lshl_b32 s94, s21, 12
	v_pk_mov_b32 v[36:37], v[202:203], v[0:1] op_sel:[1,0]
	v_fma_f32 v1, -v0, v2, v1
	v_pk_mul_f32 v[70:71], v[36:37], v[70:71]
	v_pk_mul_f32 v[94:95], v[36:37], v[94:95]
	v_sub_f32_e32 v65, v65, v70
	v_sub_f32_e32 v3, v232, v94
	v_sub_f32_e32 v94, v65, v71
	v_pk_mul_f32 v[70:71], v[36:37], v[74:75]
	v_pk_mul_f32 v[18:19], v[0:1], v[18:19]
	v_sub_f32_e32 v65, v215, v70
	v_sub_f32_e32 v74, v65, v71
	v_pk_mul_f32 v[70:71], v[36:37], v[88:89]
	v_pk_mul_f32 v[36:37], v[36:37], v[92:93]
	v_sub_f32_e32 v65, v230, v70
	v_sub_f32_e32 v36, v231, v36
	v_sub_f32_e32 v75, v65, v71
	v_sub_f32_e32 v88, v36, v37
	v_sub_f32_e32 v89, v3, v95
	v_fma_f32 v92, -v0, v64, v241
	ds_read2_b32 v[36:37], v66 offset0:7 offset1:8
	ds_read2_b32 v[64:65], v66 offset0:5 offset1:6
	ds_read2_b32 v[70:71], v66 offset0:3 offset1:4
	v_pk_mul_f32 v[2:3], v[0:1], v[30:31]
	v_pk_mul_f32 v[52:53], v[0:1], v[52:53]
	v_sub_f32_e32 v2, v234, v2
	v_sub_f32_e32 v3, v2, v3
	v_mov_b32_e32 v2, v1
	v_pk_mul_f32 v[30:31], v[2:3], v[68:69]
	v_sub_f32_e32 v18, v238, v18
	v_sub_f32_e32 v30, v94, v30
	v_pk_mul_f32 v[48:49], v[0:1], v[48:49]
	v_sub_f32_e32 v52, v236, v52
	v_pk_mul_f32 v[10:11], v[0:1], v[10:11]
	v_sub_f32_e32 v48, v235, v48
	v_sub_f32_e32 v68, v52, v53
	s_waitcnt lgkmcnt(0)
; __device__ __forceinline__ unsigned f2bf(float f) { return pk2(f, 0.f) & 0xffffu; }
; __global__ void __launch_bounds__(512, 2) fwd_megakernel(Params kp_) {
;     ...
;                                     for (int i = 1; i < 16; ++i) { const float* lr = Ls + (ib * 16 + i) * 64 + ib * 16;
; #pragma unroll
;                                         for (int j = 0; j < i; ++j) r[i] -= lr[j] * r[j]; }
; #pragma unroll
;                                     for (int i = 0; i < 16; ++i) { const int row = ib * 16 + i; X[row * 128] = r[i]; dst[row * 128] = (bf16)f2bf(isu ? r[i] : -r[i]); }
	v_pk_mul_f32 v[52:53], v[2:3], v[70:71]
	v_pk_mul_f32 v[56:57], v[0:1], v[56:57]
	v_sub_f32_e32 v70, v18, v19
	v_sub_f32_e32 v19, v30, v31
	v_mov_b32_e32 v18, v3
	v_sub_f32_e32 v10, v237, v10
	v_sub_f32_e32 v66, v48, v49
	v_sub_f32_e32 v35, v35, v56
	v_pk_mul_f32 v[30:31], v[18:19], v[216:217]
	v_pk_mul_f32 v[8:9], v[2:3], v[8:9]
	v_pk_mul_f32 v[48:49], v[2:3], v[72:73]
	v_sub_f32_e32 v35, v35, v57
	v_pk_mul_f32 v[56:57], v[2:3], v[90:91]
	v_sub_f32_e32 v69, v10, v11
	v_pk_mul_f32 v[10:11], v[2:3], v[226:227]
	v_sub_f32_e32 v30, v66, v30
	v_sub_f32_e32 v2, v92, v8
	v_sub_f32_e32 v48, v74, v48
	v_sub_f32_e32 v52, v75, v52
	v_sub_f32_e32 v10, v89, v10
	v_sub_f32_e32 v2, v2, v9
	v_sub_f32_e32 v9, v30, v31
	v_mov_b32_e32 v8, v19
	v_sub_f32_e32 v66, v48, v49
	v_sub_f32_e32 v52, v52, v53
	v_pk_mul_f32 v[48:49], v[18:19], v[58:59]
	v_sub_f32_e32 v53, v10, v11
	v_pk_mul_f32 v[10:11], v[18:19], v[20:21]
	v_pk_mul_f32 v[20:21], v[8:9], v[86:87]
	v_pk_mul_f32 v[38:39], v[18:19], v[38:39]
	v_sub_f32_e32 v35, v35, v48
	v_pk_mul_f32 v[12:13], v[18:19], v[12:13]
	v_sub_f32_e32 v10, v70, v10
	v_sub_f32_e32 v18, v66, v20
	v_sub_f32_e32 v56, v88, v56
	v_sub_f32_e32 v38, v68, v38
	v_sub_f32_e32 v35, v35, v49
	v_sub_f32_e32 v49, v10, v11
	v_sub_f32_e32 v11, v18, v21
	v_mov_b32_e32 v10, v9
	v_sub_f32_e32 v48, v56, v57
	v_sub_f32_e32 v12, v69, v12
	v_sub_f32_e32 v56, v38, v39
	v_pk_mul_f32 v[30:31], v[8:9], v[64:65]
	v_pk_mul_f32 v[38:39], v[8:9], v[62:63]
	v_pk_mul_f32 v[20:21], v[10:11], v[40:41]
	v_pk_mul_f32 v[16:17], v[8:9], v[16:17]
	v_sub_f32_e32 v30, v52, v30
	v_sub_f32_e32 v38, v48, v38
	v_sub_f32_e32 v48, v12, v13
	v_pk_mul_f32 v[12:13], v[8:9], v[224:225]
	v_sub_f32_e32 v18, v56, v20
	v_sub_f32_e32 v2, v2, v16
	v_sub_f32_e32 v12, v53, v12
	v_sub_f32_e32 v40, v30, v31
	v_pk_mul_f32 v[30:31], v[10:11], v[60:61]
	v_sub_f32_e32 v2, v2, v17
	v_sub_f32_e32 v17, v18, v21
	v_mov_b32_e32 v16, v11
	v_sub_f32_e32 v30, v35, v30
	v_sub_f32_e32 v35, v38, v39
	v_sub_f32_e32 v38, v12, v13
	v_pk_mul_f32 v[12:13], v[10:11], v[22:23]
	v_pk_mul_f32 v[20:21], v[16:17], v[36:37]
	v_pk_mul_f32 v[14:15], v[10:11], v[14:15]
	v_sub_f32_e32 v10, v49, v12
	v_sub_f32_e32 v8, v40, v20
	v_pk_mul_f32 v[22:23], v[16:17], v[54:55]
	v_sub_f32_e32 v10, v10, v13
	v_sub_f32_e32 v13, v8, v21
	v_mov_b32_e32 v12, v17
	v_sub_f32_e32 v14, v48, v14
	v_sub_f32_e32 v18, v30, v31
	v_sub_f32_e32 v22, v35, v22
	v_pk_mul_f32 v[20:21], v[12:13], v[28:29]
	v_sub_f32_e32 v30, v14, v15
	v_pk_mul_f32 v[14:15], v[16:17], v[222:223]
	v_sub_f32_e32 v8, v18, v20
	v_sub_f32_e32 v18, v22, v23
	v_pk_mul_f32 v[22:23], v[16:17], v[42:43]
	v_sub_f32_e32 v14, v38, v14
	v_sub_f32_e32 v2, v2, v22
	v_sub_f32_e32 v21, v8, v21
	v_mov_b32_e32 v20, v13
	v_sub_f32_e32 v28, v14, v15
	v_pk_mul_f32 v[14:15], v[12:13], v[24:25]
	v_sub_f32_e32 v2, v2, v23
	v_pk_mul_f32 v[22:23], v[20:21], v[50:51]
	v_pk_mul_f32 v[4:5], v[12:13], v[4:5]
	v_sub_f32_e32 v10, v10, v14
	v_sub_f32_e32 v8, v18, v22
	v_sub_f32_e32 v4, v30, v4
	v_sub_f32_e32 v10, v10, v15
	v_sub_f32_e32 v15, v8, v23
	v_mov_b32_e32 v14, v21
	v_sub_f32_e32 v12, v4, v5
	v_pk_mul_f32 v[6:7], v[14:15], v[6:7]
	v_pk_mul_f32 v[4:5], v[20:21], v[220:221]
	v_sub_f32_e32 v6, v12, v6
	v_pk_mul_f32 v[22:23], v[20:21], v[44:45]
	v_sub_f32_e32 v4, v28, v4
	v_sub_f32_e32 v2, v2, v22
	v_sub_f32_e32 v7, v6, v7
	v_mov_b32_e32 v6, v15
	v_sub_f32_e32 v8, v4, v5
	v_pk_mul_f32 v[4:5], v[14:15], v[26:27]
	v_sub_f32_e32 v2, v2, v23
	v_pk_mul_f32 v[22:23], v[6:7], v[200:201]
	v_sub_f32_e32 v4, v10, v4
	v_sub_f32_e32 v8, v8, v22
	ds_read2_b32 v[24:25], v233 offset0:13 offset1:14
	v_sub_f32_e32 v10, v4, v5
	v_sub_f32_e32 v5, v8, v23
	v_mov_b32_e32 v4, v7
	v_pk_mul_f32 v[22:23], v[4:5], v[96:97]
	v_pk_mul_f32 v[26:27], v[6:7], v[46:47]
	v_sub_f32_e32 v4, v10, v22
	v_sub_f32_e32 v2, v2, v26
	v_sub_f32_e32 v23, v4, v23
	v_mov_b32_e32 v22, v5
	v_sub_f32_e32 v2, v2, v27
	s_waitcnt lgkmcnt(0)
	v_pk_mul_f32 v[24:25], v[22:23], v[24:25]
	v_cndmask_b32_e64 v4, -v34, v34, s[12:13]
	v_sub_f32_e32 v2, v2, v24
	v_sub_f32_e32 v2, v2, v25
	v_cvt_pk_bf16_f32 v4, v4, s0
	v_lshl_add_u64 v[24:25], v[32:33], 0, s[94:95]
	global_store_short v[24:25], v4, off
	v_cndmask_b32_e64 v4, -v203, v203, s[12:13]
	v_cvt_pk_bf16_f32 v4, v4, s0
	global_store_short v[24:25], v4, off offset:16
	v_cndmask_b32_e64 v4, -v0, v0, s[12:13]
	ds_write2st64_b32 v67, v0, v1 offset0:4 offset1:6
	v_cndmask_b32_e64 v0, -v1, v1, s[12:13]
	v_cvt_pk_bf16_f32 v0, v0, s0
	global_store_short v[24:25], v0, off offset:48
	v_cndmask_b32_e64 v0, -v3, v3, s[12:13]
	v_cvt_pk_bf16_f32 v0, v0, s0
	global_store_short v[24:25], v0, off offset:256
	v_cndmask_b32_e64 v0, -v19, v19, s[12:13]
	v_cvt_pk_bf16_f32 v0, v0, s0
	global_store_short v[24:25], v0, off offset:272
	v_cndmask_b32_e64 v0, -v9, v9, s[12:13]
	v_cvt_pk_bf16_f32 v0, v0, s0
	global_store_short v[24:25], v0, off offset:288
	v_cndmask_b32_e64 v0, -v11, v11, s[12:13]
	v_cvt_pk_bf16_f32 v0, v0, s0
	global_store_short v[24:25], v0, off offset:304
	v_cndmask_b32_e64 v0, -v17, v17, s[12:13]
	v_cvt_pk_bf16_f32 v0, v0, s0
	global_store_short v[24:25], v0, off offset:512
	v_cndmask_b32_e64 v0, -v13, v13, s[12:13]
	v_cvt_pk_bf16_f32 v0, v0, s0
	global_store_short v[24:25], v0, off offset:528
	v_cndmask_b32_e64 v0, -v21, v21, s[12:13]
	v_cvt_pk_bf16_f32 v0, v0, s0
	global_store_short v[24:25], v0, off offset:544
	v_cndmask_b32_e64 v0, -v15, v15, s[12:13]
	v_cvt_pk_bf16_f32 v0, v0, s0
	global_store_short v[24:25], v0, off offset:560
	v_cndmask_b32_e64 v0, -v7, v7, s[12:13]
	v_cvt_pk_bf16_f32 v0, v0, s0
	global_store_short v[24:25], v0, off offset:768
	v_cndmask_b32_e64 v0, -v5, v5, s[12:13]
	v_cvt_pk_bf16_f32 v0, v0, s0
	global_store_short v[24:25], v0, off offset:784
	v_cndmask_b32_e64 v0, -v23, v23, s[12:13]
	v_cvt_pk_bf16_f32 v0, v0, s0
	global_store_short v[24:25], v0, off offset:800
	v_cndmask_b32_e64 v0, -v2, v2, s[12:13]
	s_add_i32 s21, s21, 1
	s_add_i32 s3, s3, 64
	s_addk_i32 s20, 0x1000
	v_cvt_pk_bf16_f32 v4, v4, s0
	v_cvt_pk_bf16_f32 v0, v0, s0
	s_cmp_eq_u32 s21, 4
	ds_write2st64_b32 v67, v34, v203 offset1:2
	global_store_short v[24:25], v4, off offset:32
	ds_write2st64_b32 v67, v3, v19 offset0:8 offset1:10
	ds_write2st64_b32 v67, v9, v11 offset0:12 offset1:14
	ds_write2st64_b32 v67, v17, v13 offset0:16 offset1:18
	ds_write2st64_b32 v67, v21, v15 offset0:20 offset1:22
	ds_write2st64_b32 v67, v7, v5 offset0:24 offset1:26
	ds_write2st64_b32 v67, v23, v2 offset0:28 offset1:30
	global_store_short v[24:25], v0, off offset:816
	s_cbranch_scc1 .LBB0_671

; __global__ void __launch_bounds__(512, 2) fwd_megakernel(Params kp_) {
;     ...
;                         for (int item = bid; item < 128; item += G) {
;                             const int xk_ = item >> 3, blk = xk_ & 7, bh = (item & 7) * 2 + (xk_ >> 3), h = bh & 3, b = bh >> 2, e0 = blk * 16;
;                             bf16* ST = (bf16*)lds; bf16* VT = ST + 16 * 136;
;                             for (int i = tid; i < 16 * 136; i += 512) ST[i] = 0;
;                             f32x4 Sacc = {0.f, 0.f, 0.f, 0.f};
;                             __syncthreads();
;                             const int rt = wave & 3; const bool lo = wave < 4;
;                             bf16x8 fa[4], fb[2], fk[2]; float uv[4]; float eg;
;     ...
;                             bf16x8 fa1[4], fb1[2], fk1[2]; float uv1[4]; float eg1;
;                             bf16x8 fa2[4], fb2[2], fk2[2]; float uv2[4]; float eg2;
;                             GS_LOAD(fa, fb, fk, uv, eg, 0); GS_LOAD(fa1, fb1, fk1, uv1, eg1, 1);
.LBB0_843:
	s_or_b64 exec, exec, s[0:1]
	v_mov_b32_e32 v172, v199
	s_waitcnt lgkmcnt(0)
	s_barrier
	v_readlane_b32 s0, v253, 20
	v_bfe_u32 v170, v172, 4, 2
	v_readfirstlane_b32 s2, v172
	v_and_b32_e32 v204, 15, v172
	v_lshlrev_b32_e32 v161, 3, v170
	v_readlane_b32 s1, v253, 21
	s_ashr_i32 s14, s2, 6
	v_lshlrev_b32_e32 v205, 2, v170
	v_mul_u32_u24_e32 v141, 0x90, v204
	s_andn2_b64 vcc, exec, s[0:1]
	v_and_b32_e32 v171, 48, v172
	v_lshlrev_b32_e32 v128, 1, v161
	s_cbranch_vccnz .LBB0_882
	s_movk_i32 s0, 0x880
	s_cmp_gt_i32 s14, 3
	v_cmp_gt_i32_e64 s[4:5], s0, v172
	s_cselect_b64 s[0:1], -1, 0
	s_cmp_lt_i32 s14, 4
	s_mov_b32 s3, 0x1c800000
	s_cselect_b32 s3, 0x1a800000, s3
	s_add_u32 s6, s86, s3
	s_addc_u32 s7, s87, 0
	s_lshl_b32 s8, s14, 4
	s_and_b32 s8, s8, 48
	v_or_b32_e32 v173, s8, v204
	v_and_b32_e32 v0, 12, v204
	v_lshlrev_b32_e32 v0, 6, v0
	v_and_b32_e32 v1, 3, v204
	v_lshl_or_b32 v0, v1, 4, v0
	v_lshl_or_b32 v0, v170, 10, v0
	v_lshl_or_b32 v0, s8, 8, v0
	v_mov_b32_e32 v1, v197
	v_lshl_add_u64 v[0:1], s[6:7], 0, v[0:1]
	v_readlane_b32 s6, v253, 14
	v_and_b32_e32 v196, 63, v172
	v_lshlrev_b32_e32 v196, 4, v196
	v_lshl_or_b32 v196, s8, 7, v196
	v_mov_b32_e32 v129, v197
	v_readlane_b32 s7, v253, 15
	v_mov_b64_e32 v[130:131], v[0:1]
	v_lshlrev_b32_e32 v2, 7, v204
	v_lshl_add_u64 v[0:1], s[6:7], 0, v[196:197]
	v_mov_b64_e32 v[132:133], v[0:1]
	v_and_b32_e32 v0, 63, v172
	v_lshlrev_b32_e32 v0, 3, v0
	v_lshl_or_b32 v0, s14, 10, v0
	v_ashrrev_i32_e32 v1, 31, v0
	v_lshlrev_b64 v[134:135], 1, v[0:1]
	v_lshl_add_u64 v[0:1], s[92:93], 0, v[134:135]
	s_movk_i32 s6, 0x110
	v_mov_b64_e32 v[136:137], v[0:1]
	v_mad_u32_u24 v0, v204, s6, 0
	v_add_u32_e32 v129, v0, v128
	s_lshl_b32 s6, s8, 1
	v_sub_u32_e32 v0, v0, v2
	s_lshl_b32 s2, s2, 5
	s_add_i32 s7, s6, 0
	v_add_u32_e32 v176, s6, v0
	v_mul_i32_i24_e32 v3, 0xffffff72, v204
	s_lshl_b32 s6, s14, 5
	s_and_b32 s2, s2, 0x1800
	v_add_u32_e32 v177, v0, v128
	v_add3_u32 v3, v0, v3, s6
	v_or_b32_e32 v0, s8, v205
	v_lshlrev_b32_e32 v5, 9, v170
	v_or_b32_e32 v2, s2, v2
	v_mul_u32_u24_e32 v1, 0x110, v204
	v_add_u32_e32 v174, 0, v128
	v_lshlrev_b32_e32 v0, 7, v0
	v_mul_u32_u24_e32 v4, 0x440, v170
	v_or3_b32 v5, s2, v5, v204
	v_and_b32_e32 v140, 63, v172
	v_lshl_or_b32 v140, v140, 4, s2
	v_lshlrev_b32_e32 v2, 1, v2
	v_add_u32_e32 v175, s7, v141
	v_add_u32_e32 v178, 0xfffffe00, v172
	v_lshl_add_u32 v179, v172, 1, 0
	v_and_b32_e32 v138, 7, v204
	v_lshlrev_b32_e32 v138, 1, v138
	v_lshl_or_b32 v138, v170, 8, v138
	v_and_b32_e32 v139, 8, v204
	v_lshl_or_b32 v138, v139, 7, v138
	v_lshl_or_b32 v138, s2, 1, v138
	v_mov_b32_e32 v139, v197
	s_nop 0
	v_and_b32_e32 v142, 0x3000, v2
	v_lshl_or_b32 v142, v170, 10, v142
	v_and_b32_e32 v143, 12, v204
	v_lshl_or_b32 v142, v143, 6, v142
	v_and_b32_e32 v143, 3, v204
	v_lshl_or_b32 v142, v143, 4, v142
	v_or_b32_e32 v142, s3, v142
	v_mov_b32_e32 v143, v197
	v_or_b32_e32 v144, s8, v170
	v_lshlrev_b32_e32 v144, 8, v144
	v_add_u32_e32 v180, v3, v4
	v_add_u32_e32 v181, v174, v1
	v_readlane_b32 s15, v254, 13
	s_mov_b32 s16, s46
	s_branch .LBB0_846

; __global__ void __launch_bounds__(512, 2) fwd_megakernel(Params kp_) {
;     ...
;                         for (int item = bid; item < 128; item += G) {
;                             const int xk_ = item >> 3, blk = xk_ & 7, bh = (item & 7) * 2 + (xk_ >> 3), h = bh & 3, b = bh >> 2, e0 = blk * 16;
;                             bf16* ST = (bf16*)lds; bf16* VT = ST + 16 * 136;
;                             for (int i = tid; i < 16 * 136; i += 512) ST[i] = 0;
;                             f32x4 Sacc = {0.f, 0.f, 0.f, 0.f};
;                             __syncthreads();
;                             const int rt = wave & 3; const bool lo = wave < 4;
;                             bf16x8 fa[4], fb[2], fk[2]; float uv[4]; float eg;
;     ...
;                             bf16x8 fa1[4], fb1[2], fk1[2]; float uv1[4]; float eg1;
;                             bf16x8 fa2[4], fb2[2], fk2[2]; float uv2[4]; float eg2;
;                             GS_LOAD(fa, fb, fk, uv, eg, 0); GS_LOAD(fa1, fb1, fk1, uv1, eg1, 1);
.LBB0_849:
	s_or_b64 exec, exec, s[2:3]
	s_lshl_b32 s3, s15, 1
	s_bfe_u32 s2, s15, 0x30001
	s_and_b32 s12, s3, 0xe0
	s_and_b32 s100, s12, 0x20
	s_lshl_b32 s100, s100, 6
	s_and_b32 s12, s12, 0xc0
	s_or_b32 s12, s12, s100
	s_lshl_b32 s3, s16, 1
	s_lshl_b32 s8, s2, 1
	s_lshl_b32 s10, s2, 12
	s_and_b32 s2, s3, 14
	s_ashr_i32 s11, s16, 6
	s_add_i32 s2, s2, s11
	s_and_b32 s17, s3, 0x70
	s_ashr_i32 s3, s2, 31
	s_lshl_b64 s[18:19], s[2:3], 20
	s_lshl_b64 s[6:7], s[2:3], 21
	v_readlane_b32 s13, v253, 18
	v_lshl_add_u64 v[0:1], v[130:131], 0, s[6:7]
	v_lshl_add_u64 v[2:3], v[136:137], 0, s[6:7]
	s_add_u32 s6, s13, s6
	v_readlane_b32 s22, v253, 19
	s_addc_u32 s7, s22, s7
	s_lshl_b32 s9, s17, 1
	s_and_b32 s100, s17, 0x10
	s_lshl_b32 s100, s100, 7
	s_and_b32 s101, s17, 0x60
	s_lshl_b32 s101, s101, 1
	s_or_b32 s101, s101, s100
	s_add_u32 s6, s6, s101
	s_waitcnt lgkmcnt(0)
	s_barrier
	global_load_dwordx4 v[60:63], v[0:1], off
	global_load_dwordx4 v[48:51], v[0:1], off offset:64
	global_load_dwordx4 v[52:55], v[0:1], off offset:128
	global_load_dwordx4 v[56:59], v[0:1], off offset:192
	v_lshl_add_u64 v[0:1], v[132:133], 0, s[18:19]
	s_addc_u32 s7, s7, 0
	v_and_b32_e32 v196, 7, v204
	v_lshlrev_b32_e32 v196, 1, v196
	v_and_b32_e32 v145, 8, v204
	v_lshl_or_b32 v196, v145, 7, v196
	global_load_dwordx4 v[40:43], v[0:1], off
	global_load_dwordx4 v[8:11], v[2:3], off
	global_load_dwordx4 v[44:47], v[0:1], off offset:1024
	global_load_dwordx4 v[12:15], v[2:3], off offset:1024
	v_lshl_add_u64 v[0:1], s[6:7], 0, v[196:197]
	v_mov_b32_e32 v145, v197
	v_lshl_add_u64 v[0:1], v[0:1], 0, v[144:145]
	global_load_ushort v2, v[0:1], off
	global_load_ushort v3, v[0:1], off offset:16
	s_lshl_b64 s[6:7], s[2:3], 9
	v_readlane_b32 s3, v253, 10
	s_add_u32 s6, s3, s6
	v_readlane_b32 s3, v253, 11
	s_addc_u32 s7, s3, s7
	s_bitset1_b32 s18, 13
	s_lshl_b64 s[20:21], s[18:19], 1
	s_add_u32 s3, s13, s20
	s_addc_u32 s13, s22, s21
	v_lshl_add_u64 v[4:5], v[132:133], 0, s[18:19]
	s_add_u32 s18, s3, s101
	s_addc_u32 s19, s13, 0
	v_lshl_add_u64 v[6:7], v[136:137], 0, s[20:21]
	s_waitcnt vmcnt(14)
	v_lshl_add_u64 v[64:65], s[18:19], 0, v[196:197]
	v_lshl_add_u64 v[66:67], v[64:65], 0, v[144:145]
	s_lshl_b32 s3, s2, 7
	s_and_b32 s18, s3, 0x180
	s_lshl_b32 s3, s18, 1
	v_lshlrev_b32_e32 v196, 1, v205
	v_mov_b32_e32 v80, 0
	v_mov_b32_e32 v81, v80
	v_mov_b32_e32 v82, v80
	v_mov_b32_e32 v83, v80
	s_waitcnt vmcnt(1)
	v_lshlrev_b32_e32 v68, 16, v2
	global_load_ushort v2, v[0:1], off offset:32
	s_nop 0
	global_load_ushort v0, v[0:1], off offset:48
	s_waitcnt vmcnt(2)
	v_lshlrev_b32_e32 v69, 16, v3
	s_waitcnt vmcnt(1)
	v_lshlrev_b32_e32 v70, 16, v2
	s_waitcnt vmcnt(0)
	v_lshlrev_b32_e32 v71, 16, v0
	v_lshl_add_u64 v[0:1], v[130:131], 0, s[20:21]
	global_load_dwordx4 v[24:27], v[0:1], off
	global_load_dwordx4 v[28:31], v[0:1], off offset:64
	global_load_dwordx4 v[32:35], v[0:1], off offset:128
	global_load_dwordx4 v[36:39], v[0:1], off offset:192
	global_load_dwordx4 v[20:23], v[4:5], off
	s_nop 0
	global_load_dwordx4 v[0:3], v[6:7], off
	global_load_dwordx4 v[16:19], v[4:5], off offset:1024
	s_nop 0
	global_load_dwordx4 v[4:7], v[6:7], off offset:1024
	s_nop 0
	global_load_ushort v64, v[66:67], off
	global_load_ushort v65, v[66:67], off offset:16
	global_load_ushort v72, v[66:67], off offset:32
	s_nop 0
	global_load_ushort v66, v[66:67], off offset:48
	s_waitcnt vmcnt(3)
	v_lshlrev_b32_e32 v64, 16, v64
	global_load_dwordx2 v[146:147], v197, s[6:7]
	v_readlane_b32 s6, v253, 53
	v_readlane_b32 s7, v253, 54
	s_add_u32 s3, s6, s3
	s_addc_u32 s7, s7, 0
	s_add_u32 s6, s3, s9
	s_addc_u32 s7, s7, 0
	v_lshl_add_u64 v[148:149], s[6:7], 0, v[196:197]
	s_add_i32 s6, s11, s8
	s_ashr_i32 s7, s6, 31
	s_lshl_b32 s3, s11, 11
	s_lshl_b64 s[20:21], s[6:7], 21
	s_add_i32 s10, s10, s3
	s_lshl_b64 s[8:9], s[6:7], 9
	s_or_b32 s12, s20, s12
	s_mov_b32 s13, s21
	s_lshl_b64 s[6:7], s[6:7], 20
	s_and_b32 s3, s10, 0xffffe000
	s_waitcnt vmcnt(3)
	v_lshlrev_b32_e32 v65, 16, v65
	s_waitcnt vmcnt(1)
	v_lshlrev_b32_e32 v67, 16, v66
	v_lshlrev_b32_e32 v66, 16, v72
	v_lshl_add_u64 v[150:151], s[12:13], 0, v[138:139]
	v_lshl_add_u64 v[152:153], v[134:135], 0, s[20:21]
	v_mov_b32_e32 v155, s7
	v_or_b32_e32 v154, s6, v140
	v_lshl_add_u64 v[156:157], v[142:143], 0, s[20:21]
	v_or_b32_e32 v158, s3, v173
	s_mov_b32 s3, -3
.LBB0_850:
	v_lshl_add_u64 v[168:169], s[86:87], 0, v[156:157]
	s_mov_b32 s6, 0x8000
	v_add_co_u32_e32 v72, vcc, s6, v168
	v_lshl_add_u64 v[166:167], s[86:87], 0, v[154:155]
	s_nop 0
	v_addc_co_u32_e32 v73, vcc, 0, v169, vcc
	s_mov_b32 s6, 0x4804000
	global_load_dwordx4 v[92:95], v[72:73], off
	global_load_dwordx4 v[96:99], v[72:73], off offset:64
	global_load_dwordx4 v[100:103], v[72:73], off offset:128
	global_load_dwordx4 v[104:107], v[72:73], off offset:192
	v_add_co_u32_e32 v72, vcc, s6, v166
	v_lshl_add_u64 v[162:163], s[86:87], 0, v[152:153]
	s_nop 0
	v_addc_co_u32_e32 v73, vcc, 0, v167, vcc
	s_mov_b32 s6, 0x2808000
	v_add_co_u32_e32 v74, vcc, s6, v162
	v_lshl_add_u64 v[164:165], s[86:87], 0, v[150:151]
	s_nop 0
	v_addc_co_u32_e32 v75, vcc, 0, v163, vcc
	s_mov_b32 s6, 0x18808000
	v_add_co_u32_e32 v108, vcc, s6, v164
	s_add_u32 s10, s86, s8
	s_nop 0
	v_addc_co_u32_e32 v109, vcc, 0, v165, vcc
	global_load_dwordx4 v[88:91], v[72:73], off
	global_load_dwordx4 v[84:87], v[72:73], off offset:1024
	global_load_dwordx4 v[76:79], v[74:75], off
	s_nop 0
	global_load_dwordx4 v[72:75], v[74:75], off offset:1024
	s_addc_u32 s11, s87, s9
	global_load_ushort v145, v[108:109], off
	global_load_ushort v182, v[108:109], off offset:16
	global_load_ushort v183, v[108:109], off offset:32
	global_load_ushort v184, v[108:109], off offset:48
	global_load_dword v160, v239, s[10:11] offset:8
	ds_read_b128 v[108:111], v129
	ds_read_b128 v[112:115], v129 offset:64
	ds_read_b128 v[116:119], v129 offset:128
	ds_read_b128 v[120:123], v129 offset:192
	v_cndmask_b32_e64 v124, 0, 1, s[0:1]
	v_cmp_ne_u32_e64 s[6:7], 1, v124
	s_andn2_b64 vcc, exec, s[0:1]
	s_mov_b64 s[12:13], -1
	s_cbranch_vccnz .LBB0_852
	s_waitcnt lgkmcnt(3)
	v_mfma_f32_16x16x32_bf16 v[124:127], v[108:111], v[60:63], 0
	s_mov_b64 s[12:13], 0
	s_waitcnt lgkmcnt(2)
	v_mfma_f32_16x16x32_bf16 v[124:127], v[112:115], v[48:51], v[124:127]
	s_waitcnt lgkmcnt(1)
	v_mfma_f32_16x16x32_bf16 v[124:127], v[116:119], v[52:55], v[124:127]
	s_waitcnt lgkmcnt(0)
	v_mfma_f32_16x16x32_bf16 v[124:127], v[120:123], v[56:59], v[124:127]

.LBB0_856:
	s_waitcnt vmcnt(13)
	v_pk_mul_f32 v[42:43], v[82:83], v[146:147] op_sel_hi:[1,0]
	v_pk_mul_f32 v[40:41], v[80:81], v[146:147] op_sel_hi:[1,0]
	s_mov_b32 s12, 0xc000
	v_add_co_u32_e32 v60, vcc, s12, v168
	s_waitcnt lgkmcnt(1)
	v_mfma_f32_16x16x32_bf16 v[8:11], v[48:51], v[8:11], v[40:43]
	v_addc_co_u32_e32 v61, vcc, 0, v169, vcc
	s_mov_b32 s12, 0x4806000
	s_waitcnt lgkmcnt(0)
	v_mfma_f32_16x16x32_bf16 v[68:71], v[52:55], v[12:15], v[8:11]
	v_add_co_u32_e32 v12, vcc, s12, v166
	s_mov_b32 s12, 0x280c000
	s_nop 0
	v_addc_co_u32_e32 v13, vcc, 0, v167, vcc
	v_add_co_u32_e32 v14, vcc, s12, v162
	s_nop 2
	v_cvt_pk_bf16_f32 v8, v68, s0
	v_addc_co_u32_e32 v15, vcc, 0, v163, vcc
	s_mov_b32 s12, 0x1880c000
	v_cvt_pk_bf16_f32 v9, v69, s0
	v_cvt_pk_bf16_f32 v10, v70, s0
	v_cvt_pk_bf16_f32 v11, v71, s0
	ds_write_b16 v180, v8
	ds_write_b16 v180, v9 offset:272
	ds_write_b16 v180, v10 offset:544
	ds_write_b16 v180, v11 offset:816
	v_add_co_u32_e32 v62, vcc, s12, v164
	s_waitcnt lgkmcnt(0)
	s_barrier
	global_load_dwordx4 v[48:51], v[60:61], off offset:64
	global_load_dwordx4 v[52:55], v[60:61], off offset:128
	v_addc_co_u32_e32 v63, vcc, 0, v165, vcc
	global_load_dwordx4 v[56:59], v[60:61], off offset:192
	global_load_dwordx4 v[40:43], v[12:13], off
	global_load_dwordx4 v[8:11], v[14:15], off
	global_load_dwordx4 v[44:47], v[12:13], off offset:1024
	s_nop 0
	global_load_dwordx4 v[12:15], v[14:15], off offset:1024
	s_nop 0
	global_load_ushort v125, v[62:63], off
	global_load_ushort v159, v[62:63], off offset:16
	global_load_ushort v126, v[62:63], off offset:32
	global_load_ushort v127, v[62:63], off offset:48
	s_nop 0
	global_load_dwordx4 v[60:63], v[60:61], off
	s_nop 0
	global_load_dword v124, v239, s[10:11] offset:12
	ds_read_b128 v[80:83], v181
	ds_read_b128 v[108:111], v181 offset:64
	ds_read_b128 v[112:115], v181 offset:128
	ds_read_b128 v[116:119], v181 offset:192
	s_and_b64 vcc, exec, s[6:7]
	s_mov_b64 s[12:13], -1
	s_cbranch_vccnz .LBB0_858
	s_waitcnt lgkmcnt(3)
	v_mfma_f32_16x16x32_bf16 v[120:123], v[80:83], v[24:27], 0
	s_mov_b64 s[12:13], 0
	s_waitcnt lgkmcnt(2)
	v_mfma_f32_16x16x32_bf16 v[120:123], v[108:111], v[28:31], v[120:123]
	s_waitcnt lgkmcnt(1)
	v_mfma_f32_16x16x32_bf16 v[120:123], v[112:115], v[32:35], v[120:123]
	s_waitcnt lgkmcnt(0)
	v_mfma_f32_16x16x32_bf16 v[120:123], v[116:119], v[36:39], v[120:123]

.LBB0_862:
	v_pk_mul_f32 v[16:17], v[146:147], v[68:69] op_sel:[1,0]
	v_pk_mul_f32 v[18:19], v[146:147], v[70:71] op_sel:[1,0]
	s_mov_b32 s12, 0x10000
	s_waitcnt lgkmcnt(1)
	v_mfma_f32_16x16x32_bf16 v[0:3], v[24:27], v[0:3], v[16:19]
	s_waitcnt lgkmcnt(0)
	v_mfma_f32_16x16x32_bf16 v[80:83], v[28:31], v[4:7], v[0:3]
	s_nop 7
	v_cvt_pk_bf16_f32 v0, v80, s0
	v_cvt_pk_bf16_f32 v1, v81, s0
	v_cvt_pk_bf16_f32 v2, v82, s0
	v_cvt_pk_bf16_f32 v3, v83, s0
	ds_write_b16 v180, v0
	ds_write_b16 v180, v1 offset:272
	ds_write_b16 v180, v2 offset:544
	ds_write_b16 v180, v3 offset:816
	v_add_co_u32_e32 v0, vcc, s12, v168
	s_waitcnt lgkmcnt(0)
	s_barrier
	s_mov_b32 s12, 0x4808000
	s_nop 0
	v_addc_co_u32_e32 v1, vcc, 0, v169, vcc
	global_load_dwordx4 v[24:27], v[0:1], off
	global_load_dwordx4 v[28:31], v[0:1], off offset:64
	global_load_dwordx4 v[32:35], v[0:1], off offset:128
	global_load_dwordx4 v[36:39], v[0:1], off offset:192
	v_add_co_u32_e32 v0, vcc, s12, v166
	s_mov_b32 s12, 0x2810000
	s_nop 0
	v_addc_co_u32_e32 v1, vcc, 0, v167, vcc
	v_add_co_u32_e32 v4, vcc, s12, v162
	s_nop 1
	v_addc_co_u32_e32 v5, vcc, 0, v163, vcc
	v_add_co_u32_e32 v64, vcc, 0x18810000, v164
	global_load_dwordx4 v[20:23], v[0:1], off
	global_load_dwordx4 v[16:19], v[0:1], off offset:1024
	s_nop 0
	global_load_dwordx4 v[0:3], v[4:5], off
	s_nop 0
	global_load_dwordx4 v[4:7], v[4:5], off offset:1024
	v_addc_co_u32_e32 v65, vcc, 0, v165, vcc
	global_load_ushort v122, v[64:65], off
	global_load_ushort v123, v[64:65], off offset:16
	global_load_ushort v120, v[64:65], off offset:32
	global_load_ushort v121, v[64:65], off offset:48
	global_load_dword v147, v239, s[10:11] offset:16
	ds_read_b128 v[64:67], v181
	ds_read_b128 v[68:71], v181 offset:64
	ds_read_b128 v[108:111], v181 offset:128
	ds_read_b128 v[112:115], v181 offset:192
	s_and_b64 vcc, exec, s[6:7]
	s_mov_b64 s[10:11], -1
	s_cbranch_vccnz .LBB0_864
	s_waitcnt vmcnt(38) lgkmcnt(3)
	v_mfma_f32_16x16x32_bf16 v[116:119], v[64:67], v[92:95], 0
	s_mov_b64 s[10:11], 0
	s_waitcnt vmcnt(37) lgkmcnt(2)
	v_mfma_f32_16x16x32_bf16 v[116:119], v[68:71], v[96:99], v[116:119]
	s_waitcnt vmcnt(36) lgkmcnt(1)
	v_mfma_f32_16x16x32_bf16 v[116:119], v[108:111], v[100:103], v[116:119]
	s_waitcnt vmcnt(35) lgkmcnt(0)
	v_mfma_f32_16x16x32_bf16 v[116:119], v[112:115], v[104:107], v[116:119]

; __global__ void __launch_bounds__(512, 2) fwd_megakernel(Params kp_) {
	.amdhsa_kernel _Z14fwd_megakernel6Params
		.amdhsa_group_segment_fixed_size 0
		.amdhsa_private_segment_fixed_size 0
		.amdhsa_kernarg_size 416
		.amdhsa_user_sgpr_count 2
		.amdhsa_user_sgpr_dispatch_ptr 0
		.amdhsa_user_sgpr_queue_ptr 0
		.amdhsa_user_sgpr_kernarg_segment_ptr 1
		.amdhsa_user_sgpr_dispatch_id 0
		.amdhsa_user_sgpr_kernarg_preload_length 0
		.amdhsa_user_sgpr_kernarg_preload_offset 0
		.amdhsa_user_sgpr_private_segment_size 0
		.amdhsa_uses_dynamic_stack 0
		.amdhsa_enable_private_segment 0
		.amdhsa_system_sgpr_workgroup_id_x 1
		.amdhsa_system_sgpr_workgroup_id_y 0
		.amdhsa_system_sgpr_workgroup_id_z 0
		.amdhsa_system_sgpr_workgroup_info 0
		.amdhsa_system_vgpr_workitem_id 2
		.amdhsa_next_free_vgpr 256
		.amdhsa_next_free_sgpr 102
		.amdhsa_accum_offset 256
		.amdhsa_reserve_vcc 1
		.amdhsa_float_round_mode_32 0
		.amdhsa_float_round_mode_16_64 0
		.amdhsa_float_denorm_mode_32 3
		.amdhsa_float_denorm_mode_16_64 3
		.amdhsa_dx10_clamp 1
		.amdhsa_ieee_mode 1
		.amdhsa_fp16_overflow 0
		.amdhsa_tg_split 0
		.amdhsa_exception_fp_ieee_invalid_op 0
		.amdhsa_exception_fp_denorm_src 0
		.amdhsa_exception_fp_ieee_div_zero 0
		.amdhsa_exception_fp_ieee_overflow 0
		.amdhsa_exception_fp_ieee_underflow 0
		.amdhsa_exception_fp_ieee_inexact 0
		.amdhsa_exception_int_div_zero 0
	.end_amdhsa_kernel

; __global__ void __launch_bounds__(512, 2) fwd_megakernel(Params kp_) {
amdhsa.kernels:
  - .agpr_count:     0
    .args:
      - .offset:         0
        .size:           160
        .value_kind:     by_value
      - .offset:         160
        .size:           4
        .value_kind:     hidden_block_count_x
      - .offset:         164
        .size:           4
        .value_kind:     hidden_block_count_y
      - .offset:         168
        .size:           4
        .value_kind:     hidden_block_count_z
      - .offset:         172
        .size:           2
        .value_kind:     hidden_group_size_x
      - .offset:         174
        .size:           2
        .value_kind:     hidden_group_size_y
      - .offset:         176
        .size:           2
        .value_kind:     hidden_group_size_z
      - .offset:         178
        .size:           2
        .value_kind:     hidden_remainder_x
      - .offset:         180
        .size:           2
        .value_kind:     hidden_remainder_y
      - .offset:         182
        .size:           2
        .value_kind:     hidden_remainder_z
      - .offset:         200
        .size:           8
        .value_kind:     hidden_global_offset_x
      - .offset:         208
        .size:           8
        .value_kind:     hidden_global_offset_y
      - .offset:         216
        .size:           8
        .value_kind:     hidden_global_offset_z
      - .offset:         224
        .size:           2
        .value_kind:     hidden_grid_dims
      - .offset:         248
        .size:           8
        .value_kind:     hidden_multigrid_sync_arg
      - .offset:         280
        .size:           4
        .value_kind:     hidden_dynamic_lds_size
    .group_segment_fixed_size: 0
    .kernarg_segment_align: 8
    .kernarg_segment_size: 416
    .language:       OpenCL C
    .language_version:
      - 2
      - 0
    .max_flat_workgroup_size: 512
    .name:           _Z14fwd_megakernel6Params
    .private_segment_fixed_size: 0
    .sgpr_count:     108
    .sgpr_spill_count: 314
    .symbol:         _Z14fwd_megakernel6Params.kd
    .uniform_work_group_size: 1
    .uses_dynamic_stack: false
    .vgpr_count:     256
    .vgpr_spill_count: 0
    .wavefront_size: 64
